# counted vmcnt waits moved from the load segment to the end of the following MFMA segment (one interval more latency budget, wait off the loader critical path)
# speedup vs baseline: 1.0023x; 1.0023x over previous
.LBB0_216:
	ds_read_b128 v[152:155], v160
	ds_read_b128 v[164:167], v160 offset:1024
	ds_read_b128 v[168:171], v160 offset:2048
	ds_read_b128 v[172:175], v160 offset:3072
	ds_read_b128 v[176:179], v161
	ds_read_b128 v[180:183], v161 offset:1024
	ds_read_b128 v[184:187], v161 offset:2048
	ds_read_b128 v[188:191], v161 offset:3072
	s_add_u32 s20, s0, 0xfff00080
	s_addc_u32 s21, s1, -1
	s_cmp_eq_u32 s30, 60
	s_cselect_b32 s23, s13, s21
	s_cselect_b32 s22, s24, s20
	s_cselect_b32 s21, s15, s29
	s_cselect_b32 s20, s25, s27
	s_add_i32 m0, s39, 0xc000
	ds_read_b128 v[192:195], v162
	ds_read_b128 v[196:199], v162 offset:1024
	ds_read_b128 v[200:203], v162 offset:2048
	ds_read_b128 v[204:207], v162 offset:3072
	ds_read_b128 v[208:211], v162 offset:4096
	ds_read_b128 v[212:215], v162 offset:5120
	ds_read_b128 v[216:219], v162 offset:6144
	ds_read_b128 v[220:223], v162 offset:7168
	global_load_lds_dwordx4 v140, s[0:1]
	s_add_i32 m0, s39, 0xe000
	s_nop 0
	global_load_lds_dwordx4 v142, s[0:1]
	s_waitcnt lgkmcnt(0)
	s_barrier
	v_mfma_f32_16x16x32_bf16 v[126:129], v[152:155], v[192:195], v[126:129]
	v_mfma_f32_16x16x32_bf16 v[126:129], v[164:167], v[196:199], v[126:129]
	v_mfma_f32_16x16x32_bf16 v[122:125], v[168:171], v[192:195], v[122:125]
	v_mfma_f32_16x16x32_bf16 v[122:125], v[172:175], v[196:199], v[122:125]
	v_mfma_f32_16x16x32_bf16 v[114:117], v[152:155], v[200:203], v[114:117]
	v_mfma_f32_16x16x32_bf16 v[114:117], v[164:167], v[204:207], v[114:117]
	v_mfma_f32_16x16x32_bf16 v[106:109], v[168:171], v[200:203], v[106:109]
	v_mfma_f32_16x16x32_bf16 v[106:109], v[172:175], v[204:207], v[106:109]
	v_mfma_f32_16x16x32_bf16 v[98:101], v[152:155], v[208:211], v[98:101]
	v_mfma_f32_16x16x32_bf16 v[98:101], v[164:167], v[212:215], v[98:101]
	v_mfma_f32_16x16x32_bf16 v[90:93], v[168:171], v[208:211], v[90:93]
	v_mfma_f32_16x16x32_bf16 v[90:93], v[172:175], v[212:215], v[90:93]
	v_mfma_f32_16x16x32_bf16 v[82:85], v[152:155], v[216:219], v[82:85]
	v_mfma_f32_16x16x32_bf16 v[82:85], v[164:167], v[220:223], v[82:85]
	v_mfma_f32_16x16x32_bf16 v[74:77], v[168:171], v[216:219], v[74:77]
	v_mfma_f32_16x16x32_bf16 v[74:77], v[172:175], v[220:223], v[74:77]
	v_mfma_f32_16x16x32_bf16 v[118:121], v[176:179], v[192:195], v[118:121]
	v_mfma_f32_16x16x32_bf16 v[118:121], v[180:183], v[196:199], v[118:121]
	v_mfma_f32_16x16x32_bf16 v[110:113], v[184:187], v[192:195], v[110:113]
	v_mfma_f32_16x16x32_bf16 v[110:113], v[188:191], v[196:199], v[110:113]
	v_mfma_f32_16x16x32_bf16 v[102:105], v[176:179], v[200:203], v[102:105]
	v_mfma_f32_16x16x32_bf16 v[102:105], v[180:183], v[204:207], v[102:105]
	v_mfma_f32_16x16x32_bf16 v[94:97], v[184:187], v[200:203], v[94:97]
	v_mfma_f32_16x16x32_bf16 v[94:97], v[188:191], v[204:207], v[94:97]
	v_mfma_f32_16x16x32_bf16 v[86:89], v[176:179], v[208:211], v[86:89]
	v_mfma_f32_16x16x32_bf16 v[86:89], v[180:183], v[212:215], v[86:89]
	v_mfma_f32_16x16x32_bf16 v[78:81], v[184:187], v[208:211], v[78:81]
	v_mfma_f32_16x16x32_bf16 v[78:81], v[188:191], v[212:215], v[78:81]
	v_mfma_f32_16x16x32_bf16 v[70:73], v[176:179], v[216:219], v[70:73]
	v_mfma_f32_16x16x32_bf16 v[70:73], v[180:183], v[220:223], v[70:73]
	v_mfma_f32_16x16x32_bf16 v[66:69], v[184:187], v[216:219], v[66:69]
	v_mfma_f32_16x16x32_bf16 v[66:69], v[188:191], v[220:223], v[66:69]
	s_waitcnt vmcnt(8)
	s_barrier
	s_add_i32 s31, s49, s38
	s_mov_b32 m0, s31
	ds_read_b128 v[192:195], v162 offset:16384
	ds_read_b128 v[196:199], v162 offset:17408
	ds_read_b128 v[200:203], v162 offset:18432
	ds_read_b128 v[204:207], v162 offset:19456
	ds_read_b128 v[208:211], v162 offset:20480
	ds_read_b128 v[212:215], v162 offset:21504
	ds_read_b128 v[216:219], v162 offset:22528
	ds_read_b128 v[220:223], v162 offset:23552
	global_load_lds_dwordx4 v132, s[20:21]
	s_add_i32 m0, s31, 0x2000
	s_add_u32 s34, s20, 0x100000
	s_addc_u32 s35, s21, 0
	s_add_i32 s31, s50, s38
	global_load_lds_dwordx4 v136, s[20:21]
	s_mov_b32 m0, s31
	global_load_lds_dwordx4 v132, s[34:35]
	s_add_i32 m0, s31, 0x2000
	s_nop 0
	global_load_lds_dwordx4 v136, s[34:35]
	s_mov_b32 m0, s39
	s_nop 0
	global_load_lds_dwordx4 v130, s[22:23]
	s_mov_b32 m0, s40
	s_nop 0
	global_load_lds_dwordx4 v134, s[22:23]
	s_waitcnt lgkmcnt(0)
	s_barrier
	v_mfma_f32_16x16x32_bf16 v[62:65], v[152:155], v[192:195], v[62:65]
	v_mfma_f32_16x16x32_bf16 v[62:65], v[164:167], v[196:199], v[62:65]
	v_mfma_f32_16x16x32_bf16 v[58:61], v[168:171], v[192:195], v[58:61]
	v_mfma_f32_16x16x32_bf16 v[58:61], v[172:175], v[196:199], v[58:61]
	v_mfma_f32_16x16x32_bf16 v[46:49], v[152:155], v[200:203], v[46:49]
	v_mfma_f32_16x16x32_bf16 v[46:49], v[164:167], v[204:207], v[46:49]
	v_mfma_f32_16x16x32_bf16 v[42:45], v[168:171], v[200:203], v[42:45]
	v_mfma_f32_16x16x32_bf16 v[42:45], v[172:175], v[204:207], v[42:45]
	v_mfma_f32_16x16x32_bf16 v[30:33], v[152:155], v[208:211], v[30:33]
	v_mfma_f32_16x16x32_bf16 v[30:33], v[164:167], v[212:215], v[30:33]
	v_mfma_f32_16x16x32_bf16 v[26:29], v[168:171], v[208:211], v[26:29]
	v_mfma_f32_16x16x32_bf16 v[26:29], v[172:175], v[212:215], v[26:29]
	v_mfma_f32_16x16x32_bf16 v[14:17], v[152:155], v[216:219], v[14:17]
	v_mfma_f32_16x16x32_bf16 v[14:17], v[164:167], v[220:223], v[14:17]
	v_mfma_f32_16x16x32_bf16 v[10:13], v[168:171], v[216:219], v[10:13]
	v_mfma_f32_16x16x32_bf16 v[10:13], v[172:175], v[220:223], v[10:13]
	v_mfma_f32_16x16x32_bf16 v[54:57], v[176:179], v[192:195], v[54:57]
	v_mfma_f32_16x16x32_bf16 v[54:57], v[180:183], v[196:199], v[54:57]
	v_mfma_f32_16x16x32_bf16 v[50:53], v[184:187], v[192:195], v[50:53]
	v_mfma_f32_16x16x32_bf16 v[50:53], v[188:191], v[196:199], v[50:53]
	v_mfma_f32_16x16x32_bf16 v[38:41], v[176:179], v[200:203], v[38:41]
	v_mfma_f32_16x16x32_bf16 v[38:41], v[180:183], v[204:207], v[38:41]
	v_mfma_f32_16x16x32_bf16 v[34:37], v[184:187], v[200:203], v[34:37]
	v_mfma_f32_16x16x32_bf16 v[34:37], v[188:191], v[204:207], v[34:37]
	v_mfma_f32_16x16x32_bf16 v[22:25], v[176:179], v[208:211], v[22:25]
	v_mfma_f32_16x16x32_bf16 v[22:25], v[180:183], v[212:215], v[22:25]
	v_mfma_f32_16x16x32_bf16 v[18:21], v[184:187], v[208:211], v[18:21]
	v_mfma_f32_16x16x32_bf16 v[18:21], v[188:191], v[212:215], v[18:21]
	v_mfma_f32_16x16x32_bf16 v[6:9], v[176:179], v[216:219], v[6:9]
	v_mfma_f32_16x16x32_bf16 v[6:9], v[180:183], v[220:223], v[6:9]
	v_mfma_f32_16x16x32_bf16 v[2:5], v[184:187], v[216:219], v[2:5]
	v_mfma_f32_16x16x32_bf16 v[2:5], v[188:191], v[220:223], v[2:5]
	s_waitcnt vmcnt(8)
	s_barrier
	s_add_i32 s31, 0, 0x18000
	s_add_i32 s33, 0, 0x1c000
	ds_read_b128 v[152:155], v246
	ds_read_b128 v[164:167], v246 offset:1024
	ds_read_b128 v[168:171], v246 offset:2048
	ds_read_b128 v[172:175], v246 offset:3072
	ds_read_b128 v[176:179], v247
	ds_read_b128 v[180:183], v247 offset:1024
	ds_read_b128 v[184:187], v247 offset:2048
	ds_read_b128 v[188:191], v247 offset:3072
	s_add_u32 s98, s22, 0x80
	s_addc_u32 s99, s23, 0
	s_add_u32 s22, s22, 0x100000
	s_addc_u32 s23, s23, 0
	s_mov_b32 m0, s41
	ds_read_b128 v[192:195], v162 offset:32768
	ds_read_b128 v[196:199], v162 offset:33792
	ds_read_b128 v[200:203], v162 offset:34816
	ds_read_b128 v[204:207], v162 offset:35840
	ds_read_b128 v[208:211], v162 offset:36864
	ds_read_b128 v[212:215], v162 offset:37888
	ds_read_b128 v[216:219], v162 offset:38912
	ds_read_b128 v[220:223], v162 offset:39936
	global_load_lds_dwordx4 v130, s[22:23]
	s_mov_b32 m0, s42
	s_nop 0
	global_load_lds_dwordx4 v134, s[22:23]
	s_waitcnt lgkmcnt(0)
	s_barrier
	v_mfma_f32_16x16x32_bf16 v[126:129], v[152:155], v[192:195], v[126:129]
	v_mfma_f32_16x16x32_bf16 v[126:129], v[164:167], v[196:199], v[126:129]
	v_mfma_f32_16x16x32_bf16 v[122:125], v[168:171], v[192:195], v[122:125]
	v_mfma_f32_16x16x32_bf16 v[122:125], v[172:175], v[196:199], v[122:125]
	v_mfma_f32_16x16x32_bf16 v[114:117], v[152:155], v[200:203], v[114:117]
	v_mfma_f32_16x16x32_bf16 v[114:117], v[164:167], v[204:207], v[114:117]
	v_mfma_f32_16x16x32_bf16 v[106:109], v[168:171], v[200:203], v[106:109]
	v_mfma_f32_16x16x32_bf16 v[106:109], v[172:175], v[204:207], v[106:109]
	v_mfma_f32_16x16x32_bf16 v[98:101], v[152:155], v[208:211], v[98:101]
	v_mfma_f32_16x16x32_bf16 v[98:101], v[164:167], v[212:215], v[98:101]
	v_mfma_f32_16x16x32_bf16 v[90:93], v[168:171], v[208:211], v[90:93]
	v_mfma_f32_16x16x32_bf16 v[90:93], v[172:175], v[212:215], v[90:93]
	v_mfma_f32_16x16x32_bf16 v[82:85], v[152:155], v[216:219], v[82:85]
	v_mfma_f32_16x16x32_bf16 v[82:85], v[164:167], v[220:223], v[82:85]
	v_mfma_f32_16x16x32_bf16 v[74:77], v[168:171], v[216:219], v[74:77]
	v_mfma_f32_16x16x32_bf16 v[74:77], v[172:175], v[220:223], v[74:77]
	v_mfma_f32_16x16x32_bf16 v[118:121], v[176:179], v[192:195], v[118:121]
	v_mfma_f32_16x16x32_bf16 v[118:121], v[180:183], v[196:199], v[118:121]
	v_mfma_f32_16x16x32_bf16 v[110:113], v[184:187], v[192:195], v[110:113]
	v_mfma_f32_16x16x32_bf16 v[110:113], v[188:191], v[196:199], v[110:113]
	v_mfma_f32_16x16x32_bf16 v[102:105], v[176:179], v[200:203], v[102:105]
	v_mfma_f32_16x16x32_bf16 v[102:105], v[180:183], v[204:207], v[102:105]
	v_mfma_f32_16x16x32_bf16 v[94:97], v[184:187], v[200:203], v[94:97]
	v_mfma_f32_16x16x32_bf16 v[94:97], v[188:191], v[204:207], v[94:97]
	v_mfma_f32_16x16x32_bf16 v[86:89], v[176:179], v[208:211], v[86:89]
	v_mfma_f32_16x16x32_bf16 v[86:89], v[180:183], v[212:215], v[86:89]
	v_mfma_f32_16x16x32_bf16 v[78:81], v[184:187], v[208:211], v[78:81]
	v_mfma_f32_16x16x32_bf16 v[78:81], v[188:191], v[212:215], v[78:81]
	v_mfma_f32_16x16x32_bf16 v[70:73], v[176:179], v[216:219], v[70:73]
	v_mfma_f32_16x16x32_bf16 v[70:73], v[180:183], v[220:223], v[70:73]
	v_mfma_f32_16x16x32_bf16 v[66:69], v[184:187], v[216:219], v[66:69]
	v_mfma_f32_16x16x32_bf16 v[66:69], v[188:191], v[220:223], v[66:69]
	s_waitcnt vmcnt(8)
	s_barrier
	s_add_i32 s22, s31, s38
	s_mov_b32 m0, s22
	ds_read_b128 v[192:195], v162 offset:49152
	ds_read_b128 v[196:199], v162 offset:50176
	ds_read_b128 v[200:203], v162 offset:51200
	ds_read_b128 v[204:207], v162 offset:52224
	ds_read_b128 v[208:211], v162 offset:53248
	ds_read_b128 v[212:215], v162 offset:54272
	ds_read_b128 v[216:219], v162 offset:55296
	ds_read_b128 v[220:223], v162 offset:56320
	s_add_u32 s20, s20, 0x80
	s_addc_u32 s21, s21, 0
	global_load_lds_dwordx4 v132, s[20:21]
	s_add_i32 m0, s22, 0x2000
	s_add_i32 s22, s33, s38
	global_load_lds_dwordx4 v136, s[20:21]
	s_add_u32 s20, s20, 0x100000
	s_addc_u32 s21, s21, 0
	s_mov_b32 m0, s22
	s_nop 0
	global_load_lds_dwordx4 v132, s[20:21]
	s_add_i32 m0, s22, 0x2000
	s_nop 0
	global_load_lds_dwordx4 v136, s[20:21]
	s_mov_b32 m0, s45
	s_nop 0
	global_load_lds_dwordx4 v130, s[98:99]
	s_mov_b32 m0, s46
	s_nop 0
	global_load_lds_dwordx4 v134, s[98:99]
	s_waitcnt lgkmcnt(0)
	s_barrier
	v_mfma_f32_16x16x32_bf16 v[62:65], v[152:155], v[192:195], v[62:65]
	v_mfma_f32_16x16x32_bf16 v[62:65], v[164:167], v[196:199], v[62:65]
	v_mfma_f32_16x16x32_bf16 v[58:61], v[168:171], v[192:195], v[58:61]
	v_mfma_f32_16x16x32_bf16 v[58:61], v[172:175], v[196:199], v[58:61]
	v_mfma_f32_16x16x32_bf16 v[46:49], v[152:155], v[200:203], v[46:49]
	v_mfma_f32_16x16x32_bf16 v[46:49], v[164:167], v[204:207], v[46:49]
	v_mfma_f32_16x16x32_bf16 v[42:45], v[168:171], v[200:203], v[42:45]
	v_mfma_f32_16x16x32_bf16 v[42:45], v[172:175], v[204:207], v[42:45]
	v_mfma_f32_16x16x32_bf16 v[30:33], v[152:155], v[208:211], v[30:33]
	v_mfma_f32_16x16x32_bf16 v[30:33], v[164:167], v[212:215], v[30:33]
	v_mfma_f32_16x16x32_bf16 v[26:29], v[168:171], v[208:211], v[26:29]
	v_mfma_f32_16x16x32_bf16 v[26:29], v[172:175], v[212:215], v[26:29]
	v_mfma_f32_16x16x32_bf16 v[14:17], v[152:155], v[216:219], v[14:17]
	v_mfma_f32_16x16x32_bf16 v[14:17], v[164:167], v[220:223], v[14:17]
	v_mfma_f32_16x16x32_bf16 v[10:13], v[168:171], v[216:219], v[10:13]
	v_mfma_f32_16x16x32_bf16 v[10:13], v[172:175], v[220:223], v[10:13]
	v_mfma_f32_16x16x32_bf16 v[54:57], v[176:179], v[192:195], v[54:57]
	v_mfma_f32_16x16x32_bf16 v[54:57], v[180:183], v[196:199], v[54:57]
	v_mfma_f32_16x16x32_bf16 v[50:53], v[184:187], v[192:195], v[50:53]
	v_mfma_f32_16x16x32_bf16 v[50:53], v[188:191], v[196:199], v[50:53]
	v_mfma_f32_16x16x32_bf16 v[38:41], v[176:179], v[200:203], v[38:41]
	v_mfma_f32_16x16x32_bf16 v[38:41], v[180:183], v[204:207], v[38:41]
	v_mfma_f32_16x16x32_bf16 v[34:37], v[184:187], v[200:203], v[34:37]
	v_mfma_f32_16x16x32_bf16 v[34:37], v[188:191], v[204:207], v[34:37]
	v_mfma_f32_16x16x32_bf16 v[22:25], v[176:179], v[208:211], v[22:25]
	v_mfma_f32_16x16x32_bf16 v[22:25], v[180:183], v[212:215], v[22:25]
	v_mfma_f32_16x16x32_bf16 v[18:21], v[184:187], v[208:211], v[18:21]
	v_mfma_f32_16x16x32_bf16 v[18:21], v[188:191], v[212:215], v[18:21]
	v_mfma_f32_16x16x32_bf16 v[6:9], v[176:179], v[216:219], v[6:9]
	v_mfma_f32_16x16x32_bf16 v[6:9], v[180:183], v[220:223], v[6:9]
	v_mfma_f32_16x16x32_bf16 v[2:5], v[184:187], v[216:219], v[2:5]
	v_mfma_f32_16x16x32_bf16 v[2:5], v[188:191], v[220:223], v[2:5]
	s_waitcnt vmcnt(8)
	s_barrier
	s_add_i32 s30, s30, 2
	s_add_u32 s0, s0, 0x100
	s_addc_u32 s1, s1, 0
	s_add_u32 s27, s27, 0x100
	s_addc_u32 s29, s29, 0
	s_cmp_gt_u32 s30, 61
	s_cbranch_scc0 .LBB0_216
	s_and_b64 vcc, exec, s[10:11]
	s_cbranch_vccz .LBB0_219
	s_barrier

.LBB0_271:
	ds_read_b128 v[26:29], v183
	ds_read_b128 v[30:33], v183 offset:1024
	ds_read_b128 v[18:21], v183 offset:2048
	ds_read_b128 v[22:25], v183 offset:3072
	ds_read_b128 v[10:13], v184
	ds_read_b128 v[14:17], v184 offset:1024
	ds_read_b128 v[2:5], v184 offset:2048
	ds_read_b128 v[6:9], v184 offset:3072
	s_add_u32 s0, s20, 0xfff80080
	s_addc_u32 s1, s21, -1
	s_cmp_eq_u32 s29, 28
	s_cselect_b32 s23, s13, s1
	s_cselect_b32 s22, s25, s0
	s_cselect_b32 s1, s11, s28
	s_cselect_b32 s0, s26, s27
	s_add_i32 m0, s19, 0xc000
	ds_read_b128 v[174:177], v185
	ds_read_b128 v[178:181], v185 offset:1024
	ds_read_b128 v[188:191], v185 offset:2048
	ds_read_b128 v[192:195], v185 offset:3072
	ds_read_b128 v[196:199], v185 offset:4096
	ds_read_b128 v[200:203], v185 offset:5120
	ds_read_b128 v[204:207], v185 offset:6144
	ds_read_b128 v[208:211], v185 offset:7168
	global_load_lds_dwordx4 v162, s[20:21]
	s_add_i32 m0, s19, 0xe000
	s_nop 0
	global_load_lds_dwordx4 v172, s[20:21]
	s_waitcnt lgkmcnt(0)
	s_barrier
	v_mfma_f32_16x16x128_f8f6f4 v[158:161], v[26:33], v[174:181], v[158:161]
	v_mfma_f32_16x16x128_f8f6f4 v[154:157], v[18:25], v[174:181], v[154:157]
	v_mfma_f32_16x16x128_f8f6f4 v[146:149], v[26:33], v[188:195], v[146:149]
	v_mfma_f32_16x16x128_f8f6f4 v[138:141], v[18:25], v[188:195], v[138:141]
	v_mfma_f32_16x16x128_f8f6f4 v[130:133], v[26:33], v[196:203], v[130:133]
	v_mfma_f32_16x16x128_f8f6f4 v[122:125], v[18:25], v[196:203], v[122:125]
	v_mfma_f32_16x16x128_f8f6f4 v[114:117], v[26:33], v[204:211], v[114:117]
	v_mfma_f32_16x16x128_f8f6f4 v[106:109], v[18:25], v[204:211], v[106:109]
	v_mfma_f32_16x16x128_f8f6f4 v[150:153], v[10:17], v[174:181], v[150:153]
	v_mfma_f32_16x16x128_f8f6f4 v[142:145], v[2:9], v[174:181], v[142:145]
	v_mfma_f32_16x16x128_f8f6f4 v[134:137], v[10:17], v[188:195], v[134:137]
	v_mfma_f32_16x16x128_f8f6f4 v[126:129], v[2:9], v[188:195], v[126:129]
	v_mfma_f32_16x16x128_f8f6f4 v[118:121], v[10:17], v[196:203], v[118:121]
	v_mfma_f32_16x16x128_f8f6f4 v[110:113], v[2:9], v[196:203], v[110:113]
	v_mfma_f32_16x16x128_f8f6f4 v[102:105], v[10:17], v[204:211], v[102:105]
	v_mfma_f32_16x16x128_f8f6f4 v[98:101], v[2:9], v[204:211], v[98:101]
	s_waitcnt vmcnt(8)
	s_barrier
	s_add_i32 s30, s48, s37
	s_mov_b32 m0, s30
	ds_read_b128 v[188:191], v185 offset:16384
	ds_read_b128 v[192:195], v185 offset:17408
	ds_read_b128 v[196:199], v185 offset:18432
	ds_read_b128 v[200:203], v185 offset:19456
	ds_read_b128 v[204:207], v185 offset:20480
	ds_read_b128 v[208:211], v185 offset:21504
	ds_read_b128 v[212:215], v185 offset:22528
	ds_read_b128 v[216:219], v185 offset:23552
	global_load_lds_dwordx4 v168, s[0:1]
	s_add_i32 m0, s30, 0x2000
	s_add_u32 s30, s0, 0x80000
	s_addc_u32 s31, s1, 0
	s_add_i32 s33, s49, s37
	global_load_lds_dwordx4 v170, s[0:1]
	s_mov_b32 m0, s33
	global_load_lds_dwordx4 v168, s[30:31]
	s_add_i32 m0, s33, 0x2000
	s_nop 0
	global_load_lds_dwordx4 v170, s[30:31]
	s_mov_b32 m0, s19
	s_nop 0
	global_load_lds_dwordx4 v162, s[22:23]
	s_mov_b32 m0, s38
	s_nop 0
	global_load_lds_dwordx4 v172, s[22:23]
	s_waitcnt lgkmcnt(0)
	s_barrier
	v_mfma_f32_16x16x128_f8f6f4 v[94:97], v[26:33], v[188:195], v[94:97]
	v_mfma_f32_16x16x128_f8f6f4 v[90:93], v[18:25], v[188:195], v[90:93]
	v_mfma_f32_16x16x128_f8f6f4 v[78:81], v[26:33], v[196:203], v[78:81]
	v_mfma_f32_16x16x128_f8f6f4 v[74:77], v[18:25], v[196:203], v[74:77]
	v_mfma_f32_16x16x128_f8f6f4 v[62:65], v[26:33], v[204:211], v[62:65]
	v_mfma_f32_16x16x128_f8f6f4 v[58:61], v[18:25], v[204:211], v[58:61]
	v_mfma_f32_16x16x128_f8f6f4 v[46:49], v[26:33], v[212:219], v[46:49]
	v_mfma_f32_16x16x128_f8f6f4 v[42:45], v[18:25], v[212:219], v[42:45]
	v_mfma_f32_16x16x128_f8f6f4 v[86:89], v[10:17], v[188:195], v[86:89]
	v_mfma_f32_16x16x128_f8f6f4 v[82:85], v[2:9], v[188:195], v[82:85]
	v_mfma_f32_16x16x128_f8f6f4 v[70:73], v[10:17], v[196:203], v[70:73]
	v_mfma_f32_16x16x128_f8f6f4 v[66:69], v[2:9], v[196:203], v[66:69]
	v_mfma_f32_16x16x128_f8f6f4 v[54:57], v[10:17], v[204:211], v[54:57]
	v_mfma_f32_16x16x128_f8f6f4 v[50:53], v[2:9], v[204:211], v[50:53]
	v_mfma_f32_16x16x128_f8f6f4 v[38:41], v[10:17], v[212:219], v[38:41]
	v_mfma_f32_16x16x128_f8f6f4 v[34:37], v[2:9], v[212:219], v[34:37]
	s_waitcnt vmcnt(8)
	s_barrier
	s_add_i32 s30, 0, 0x18000
	s_add_i32 s31, 0, 0x1c000
	ds_read_b128 v[2:5], v246
	ds_read_b128 v[6:9], v246 offset:1024
	ds_read_b128 v[10:13], v246 offset:2048
	ds_read_b128 v[14:17], v246 offset:3072
	ds_read_b128 v[18:21], v247
	ds_read_b128 v[22:25], v247 offset:1024
	ds_read_b128 v[26:29], v247 offset:2048
	ds_read_b128 v[30:33], v247 offset:3072
	s_add_u32 s98, s22, 0x80
	s_addc_u32 s99, s23, 0
	s_add_u32 s22, s22, 0x80000
	s_addc_u32 s23, s23, 0
	s_mov_b32 m0, s39
	ds_read_b128 v[188:191], v185 offset:32768
	ds_read_b128 v[192:195], v185 offset:33792
	ds_read_b128 v[196:199], v185 offset:34816
	ds_read_b128 v[200:203], v185 offset:35840
	ds_read_b128 v[204:207], v185 offset:36864
	ds_read_b128 v[208:211], v185 offset:37888
	ds_read_b128 v[212:215], v185 offset:38912
	ds_read_b128 v[216:219], v185 offset:39936
	global_load_lds_dwordx4 v162, s[22:23]
	s_mov_b32 m0, s40
	s_nop 0
	global_load_lds_dwordx4 v172, s[22:23]
	s_waitcnt lgkmcnt(0)
	s_barrier
	v_mfma_f32_16x16x128_f8f6f4 v[158:161], v[2:9], v[188:195], v[158:161]
	v_mfma_f32_16x16x128_f8f6f4 v[154:157], v[10:17], v[188:195], v[154:157]
	v_mfma_f32_16x16x128_f8f6f4 v[146:149], v[2:9], v[196:203], v[146:149]
	v_mfma_f32_16x16x128_f8f6f4 v[138:141], v[10:17], v[196:203], v[138:141]
	v_mfma_f32_16x16x128_f8f6f4 v[130:133], v[2:9], v[204:211], v[130:133]
	v_mfma_f32_16x16x128_f8f6f4 v[122:125], v[10:17], v[204:211], v[122:125]
	v_mfma_f32_16x16x128_f8f6f4 v[114:117], v[2:9], v[212:219], v[114:117]
	v_mfma_f32_16x16x128_f8f6f4 v[106:109], v[10:17], v[212:219], v[106:109]
	v_mfma_f32_16x16x128_f8f6f4 v[150:153], v[18:25], v[188:195], v[150:153]
	v_mfma_f32_16x16x128_f8f6f4 v[142:145], v[26:33], v[188:195], v[142:145]
	v_mfma_f32_16x16x128_f8f6f4 v[134:137], v[18:25], v[196:203], v[134:137]
	v_mfma_f32_16x16x128_f8f6f4 v[126:129], v[26:33], v[196:203], v[126:129]
	v_mfma_f32_16x16x128_f8f6f4 v[118:121], v[18:25], v[204:211], v[118:121]
	v_mfma_f32_16x16x128_f8f6f4 v[110:113], v[26:33], v[204:211], v[110:113]
	v_mfma_f32_16x16x128_f8f6f4 v[102:105], v[18:25], v[212:219], v[102:105]
	v_mfma_f32_16x16x128_f8f6f4 v[98:101], v[26:33], v[212:219], v[98:101]
	s_waitcnt vmcnt(8)
	s_barrier
	s_add_i32 s22, s30, s37
	s_mov_b32 m0, s22
	ds_read_b128 v[188:191], v185 offset:49152
	ds_read_b128 v[192:195], v185 offset:50176
	ds_read_b128 v[196:199], v185 offset:51200
	ds_read_b128 v[200:203], v185 offset:52224
	ds_read_b128 v[204:207], v185 offset:53248
	ds_read_b128 v[208:211], v185 offset:54272
	ds_read_b128 v[212:215], v185 offset:55296
	ds_read_b128 v[216:219], v185 offset:56320
	s_add_u32 s0, s0, 0x80
	s_addc_u32 s1, s1, 0
	global_load_lds_dwordx4 v168, s[0:1]
	s_add_i32 m0, s22, 0x2000
	s_add_i32 s22, s31, s37
	global_load_lds_dwordx4 v170, s[0:1]
	s_add_u32 s0, s0, 0x80000
	s_addc_u32 s1, s1, 0
	s_mov_b32 m0, s22
	s_nop 0
	global_load_lds_dwordx4 v168, s[0:1]
	s_add_i32 m0, s22, 0x2000
	s_nop 0
	global_load_lds_dwordx4 v170, s[0:1]
	s_mov_b32 m0, s44
	s_nop 0
	global_load_lds_dwordx4 v162, s[98:99]
	s_mov_b32 m0, s45
	s_nop 0
	global_load_lds_dwordx4 v172, s[98:99]
	s_waitcnt lgkmcnt(0)
	s_barrier
	v_mfma_f32_16x16x128_f8f6f4 v[94:97], v[2:9], v[188:195], v[94:97]
	v_mfma_f32_16x16x128_f8f6f4 v[90:93], v[10:17], v[188:195], v[90:93]
	v_mfma_f32_16x16x128_f8f6f4 v[78:81], v[2:9], v[196:203], v[78:81]
	v_mfma_f32_16x16x128_f8f6f4 v[74:77], v[10:17], v[196:203], v[74:77]
	v_mfma_f32_16x16x128_f8f6f4 v[62:65], v[2:9], v[204:211], v[62:65]
	v_mfma_f32_16x16x128_f8f6f4 v[58:61], v[10:17], v[204:211], v[58:61]
	v_mfma_f32_16x16x128_f8f6f4 v[46:49], v[2:9], v[212:219], v[46:49]
	v_mfma_f32_16x16x128_f8f6f4 v[42:45], v[10:17], v[212:219], v[42:45]
	v_mfma_f32_16x16x128_f8f6f4 v[86:89], v[18:25], v[188:195], v[86:89]
	v_mfma_f32_16x16x128_f8f6f4 v[82:85], v[26:33], v[188:195], v[82:85]
	v_mfma_f32_16x16x128_f8f6f4 v[70:73], v[18:25], v[196:203], v[70:73]
	v_mfma_f32_16x16x128_f8f6f4 v[66:69], v[26:33], v[196:203], v[66:69]
	v_mfma_f32_16x16x128_f8f6f4 v[54:57], v[18:25], v[204:211], v[54:57]
	v_mfma_f32_16x16x128_f8f6f4 v[50:53], v[26:33], v[204:211], v[50:53]
	v_mfma_f32_16x16x128_f8f6f4 v[38:41], v[18:25], v[212:219], v[38:41]
	v_mfma_f32_16x16x128_f8f6f4 v[34:37], v[26:33], v[212:219], v[34:37]
	s_waitcnt vmcnt(8)
	s_barrier
	s_add_i32 s29, s29, 2
	s_add_u32 s20, s20, 0x100
	s_addc_u32 s21, s21, 0
	s_add_u32 s27, s27, 0x100
	s_addc_u32 s28, s28, 0
	s_cmp_gt_u32 s29, 29
	s_cbranch_scc0 .LBB0_271
	s_and_b64 vcc, exec, s[8:9]
	s_cbranch_vccz .LBB0_274
	s_barrier

.LBB0_839:
	ds_read_b128 v[26:29], v183
	ds_read_b128 v[30:33], v183 offset:1024
	ds_read_b128 v[18:21], v183 offset:2048
	ds_read_b128 v[22:25], v183 offset:3072
	ds_read_b128 v[10:13], v184
	ds_read_b128 v[14:17], v184 offset:1024
	ds_read_b128 v[2:5], v184 offset:2048
	ds_read_b128 v[6:9], v184 offset:3072
	s_add_u32 s30, s28, 0xfffc0080
	s_addc_u32 s31, s29, -1
	s_cmp_eq_u32 s53, 12
	s_cselect_b32 s35, s21, s31
	s_cselect_b32 s34, s49, s30
	s_cselect_b32 s31, s19, s52
	s_cselect_b32 s30, s50, s51
	s_add_i32 m0, s27, 0xc000
	ds_read_b128 v[174:177], v185
	ds_read_b128 v[178:181], v185 offset:1024
	ds_read_b128 v[188:191], v185 offset:2048
	ds_read_b128 v[192:195], v185 offset:3072
	ds_read_b128 v[196:199], v185 offset:4096
	ds_read_b128 v[200:203], v185 offset:5120
	ds_read_b128 v[204:207], v185 offset:6144
	ds_read_b128 v[208:211], v185 offset:7168
	global_load_lds_dwordx4 v162, s[28:29]
	s_add_i32 m0, s27, 0xe000
	s_nop 0
	global_load_lds_dwordx4 v172, s[28:29]
	s_waitcnt lgkmcnt(0)
	s_barrier
	v_mfma_f32_16x16x128_f8f6f4 v[158:161], v[26:33], v[174:181], v[158:161]
	v_mfma_f32_16x16x128_f8f6f4 v[154:157], v[18:25], v[174:181], v[154:157]
	v_mfma_f32_16x16x128_f8f6f4 v[142:145], v[26:33], v[188:195], v[142:145]
	v_mfma_f32_16x16x128_f8f6f4 v[138:141], v[18:25], v[188:195], v[138:141]
	v_mfma_f32_16x16x128_f8f6f4 v[126:129], v[26:33], v[196:203], v[126:129]
	v_mfma_f32_16x16x128_f8f6f4 v[122:125], v[18:25], v[196:203], v[122:125]
	v_mfma_f32_16x16x128_f8f6f4 v[110:113], v[26:33], v[204:211], v[110:113]
	v_mfma_f32_16x16x128_f8f6f4 v[106:109], v[18:25], v[204:211], v[106:109]
	v_mfma_f32_16x16x128_f8f6f4 v[150:153], v[10:17], v[174:181], v[150:153]
	v_mfma_f32_16x16x128_f8f6f4 v[146:149], v[2:9], v[174:181], v[146:149]
	v_mfma_f32_16x16x128_f8f6f4 v[134:137], v[10:17], v[188:195], v[134:137]
	v_mfma_f32_16x16x128_f8f6f4 v[130:133], v[2:9], v[188:195], v[130:133]
	v_mfma_f32_16x16x128_f8f6f4 v[118:121], v[10:17], v[196:203], v[118:121]
	v_mfma_f32_16x16x128_f8f6f4 v[114:117], v[2:9], v[196:203], v[114:117]
	v_mfma_f32_16x16x128_f8f6f4 v[102:105], v[10:17], v[204:211], v[102:105]
	v_mfma_f32_16x16x128_f8f6f4 v[98:101], v[2:9], v[204:211], v[98:101]
	s_waitcnt vmcnt(8)
	s_barrier
	s_add_i32 s54, s46, s36
	s_mov_b32 m0, s54
	ds_read_b128 v[188:191], v185 offset:16384
	ds_read_b128 v[192:195], v185 offset:17408
	ds_read_b128 v[196:199], v185 offset:18432
	ds_read_b128 v[200:203], v185 offset:19456
	ds_read_b128 v[204:207], v185 offset:20480
	ds_read_b128 v[208:211], v185 offset:21504
	ds_read_b128 v[212:215], v185 offset:22528
	ds_read_b128 v[216:219], v185 offset:23552
	global_load_lds_dwordx4 v168, s[30:31]
	s_add_i32 m0, s54, 0x2000
	s_add_u32 s54, s30, 0x40000
	s_addc_u32 s55, s31, 0
	s_add_i32 s56, s47, s36
	global_load_lds_dwordx4 v170, s[30:31]
	s_mov_b32 m0, s56
	global_load_lds_dwordx4 v168, s[54:55]
	s_add_i32 m0, s56, 0x2000
	s_nop 0
	global_load_lds_dwordx4 v170, s[54:55]
	s_mov_b32 m0, s27
	s_nop 0
	global_load_lds_dwordx4 v162, s[34:35]
	s_mov_b32 m0, s37
	s_nop 0
	global_load_lds_dwordx4 v172, s[34:35]
	s_waitcnt lgkmcnt(0)
	s_barrier
	v_mfma_f32_16x16x128_f8f6f4 v[94:97], v[26:33], v[188:195], v[94:97]
	v_mfma_f32_16x16x128_f8f6f4 v[90:93], v[18:25], v[188:195], v[90:93]
	v_mfma_f32_16x16x128_f8f6f4 v[78:81], v[26:33], v[196:203], v[78:81]
	v_mfma_f32_16x16x128_f8f6f4 v[74:77], v[18:25], v[196:203], v[74:77]
	v_mfma_f32_16x16x128_f8f6f4 v[62:65], v[26:33], v[204:211], v[62:65]
	v_mfma_f32_16x16x128_f8f6f4 v[58:61], v[18:25], v[204:211], v[58:61]
	v_mfma_f32_16x16x128_f8f6f4 v[46:49], v[26:33], v[212:219], v[46:49]
	v_mfma_f32_16x16x128_f8f6f4 v[42:45], v[18:25], v[212:219], v[42:45]
	v_mfma_f32_16x16x128_f8f6f4 v[86:89], v[10:17], v[188:195], v[86:89]
	v_mfma_f32_16x16x128_f8f6f4 v[82:85], v[2:9], v[188:195], v[82:85]
	v_mfma_f32_16x16x128_f8f6f4 v[70:73], v[10:17], v[196:203], v[70:73]
	v_mfma_f32_16x16x128_f8f6f4 v[66:69], v[2:9], v[196:203], v[66:69]
	v_mfma_f32_16x16x128_f8f6f4 v[54:57], v[10:17], v[204:211], v[54:57]
	v_mfma_f32_16x16x128_f8f6f4 v[50:53], v[2:9], v[204:211], v[50:53]
	v_mfma_f32_16x16x128_f8f6f4 v[38:41], v[10:17], v[212:219], v[38:41]
	v_mfma_f32_16x16x128_f8f6f4 v[34:37], v[2:9], v[212:219], v[34:37]
	s_waitcnt vmcnt(8)
	s_barrier
	s_add_i32 s54, 0, 0x18000
	s_add_i32 s55, 0, 0x1c000
	ds_read_b128 v[2:5], v246
	ds_read_b128 v[6:9], v246 offset:1024
	ds_read_b128 v[10:13], v246 offset:2048
	ds_read_b128 v[14:17], v246 offset:3072
	ds_read_b128 v[18:21], v247
	ds_read_b128 v[22:25], v247 offset:1024
	ds_read_b128 v[26:29], v247 offset:2048
	ds_read_b128 v[30:33], v247 offset:3072
	s_add_u32 s98, s34, 0x80
	s_addc_u32 s99, s35, 0
	s_add_u32 s34, s34, 0x40000
	s_addc_u32 s35, s35, 0
	s_mov_b32 m0, s38
	ds_read_b128 v[188:191], v185 offset:32768
	ds_read_b128 v[192:195], v185 offset:33792
	ds_read_b128 v[196:199], v185 offset:34816
	ds_read_b128 v[200:203], v185 offset:35840
	ds_read_b128 v[204:207], v185 offset:36864
	ds_read_b128 v[208:211], v185 offset:37888
	ds_read_b128 v[212:215], v185 offset:38912
	ds_read_b128 v[216:219], v185 offset:39936
	global_load_lds_dwordx4 v162, s[34:35]
	s_mov_b32 m0, s39
	s_nop 0
	global_load_lds_dwordx4 v172, s[34:35]
	s_waitcnt lgkmcnt(0)
	s_barrier
	v_mfma_f32_16x16x128_f8f6f4 v[158:161], v[2:9], v[188:195], v[158:161]
	v_mfma_f32_16x16x128_f8f6f4 v[154:157], v[10:17], v[188:195], v[154:157]
	v_mfma_f32_16x16x128_f8f6f4 v[142:145], v[2:9], v[196:203], v[142:145]
	v_mfma_f32_16x16x128_f8f6f4 v[138:141], v[10:17], v[196:203], v[138:141]
	v_mfma_f32_16x16x128_f8f6f4 v[126:129], v[2:9], v[204:211], v[126:129]
	v_mfma_f32_16x16x128_f8f6f4 v[122:125], v[10:17], v[204:211], v[122:125]
	v_mfma_f32_16x16x128_f8f6f4 v[110:113], v[2:9], v[212:219], v[110:113]
	v_mfma_f32_16x16x128_f8f6f4 v[106:109], v[10:17], v[212:219], v[106:109]
	v_mfma_f32_16x16x128_f8f6f4 v[150:153], v[18:25], v[188:195], v[150:153]
	v_mfma_f32_16x16x128_f8f6f4 v[146:149], v[26:33], v[188:195], v[146:149]
	v_mfma_f32_16x16x128_f8f6f4 v[134:137], v[18:25], v[196:203], v[134:137]
	v_mfma_f32_16x16x128_f8f6f4 v[130:133], v[26:33], v[196:203], v[130:133]
	v_mfma_f32_16x16x128_f8f6f4 v[118:121], v[18:25], v[204:211], v[118:121]
	v_mfma_f32_16x16x128_f8f6f4 v[114:117], v[26:33], v[204:211], v[114:117]
	v_mfma_f32_16x16x128_f8f6f4 v[102:105], v[18:25], v[212:219], v[102:105]
	v_mfma_f32_16x16x128_f8f6f4 v[98:101], v[26:33], v[212:219], v[98:101]
	s_waitcnt vmcnt(8)
	s_barrier
	s_add_i32 s34, s54, s36
	s_mov_b32 m0, s34
	ds_read_b128 v[188:191], v185 offset:49152
	ds_read_b128 v[192:195], v185 offset:50176
	ds_read_b128 v[196:199], v185 offset:51200
	ds_read_b128 v[200:203], v185 offset:52224
	ds_read_b128 v[204:207], v185 offset:53248
	ds_read_b128 v[208:211], v185 offset:54272
	ds_read_b128 v[212:215], v185 offset:55296
	ds_read_b128 v[216:219], v185 offset:56320
	s_add_u32 s30, s30, 0x80
	s_addc_u32 s31, s31, 0
	global_load_lds_dwordx4 v168, s[30:31]
	s_add_i32 m0, s34, 0x2000
	s_add_i32 s34, s55, s36
	global_load_lds_dwordx4 v170, s[30:31]
	s_add_u32 s30, s30, 0x40000
	s_addc_u32 s31, s31, 0
	s_mov_b32 m0, s34
	s_nop 0
	global_load_lds_dwordx4 v168, s[30:31]
	s_add_i32 m0, s34, 0x2000
	s_nop 0
	global_load_lds_dwordx4 v170, s[30:31]
	s_mov_b32 m0, s43
	s_nop 0
	global_load_lds_dwordx4 v162, s[98:99]
	s_mov_b32 m0, s44
	s_nop 0
	global_load_lds_dwordx4 v172, s[98:99]
	s_waitcnt lgkmcnt(0)
	s_barrier
	v_mfma_f32_16x16x128_f8f6f4 v[94:97], v[2:9], v[188:195], v[94:97]
	v_mfma_f32_16x16x128_f8f6f4 v[90:93], v[10:17], v[188:195], v[90:93]
	v_mfma_f32_16x16x128_f8f6f4 v[78:81], v[2:9], v[196:203], v[78:81]
	v_mfma_f32_16x16x128_f8f6f4 v[74:77], v[10:17], v[196:203], v[74:77]
	v_mfma_f32_16x16x128_f8f6f4 v[62:65], v[2:9], v[204:211], v[62:65]
	v_mfma_f32_16x16x128_f8f6f4 v[58:61], v[10:17], v[204:211], v[58:61]
	v_mfma_f32_16x16x128_f8f6f4 v[46:49], v[2:9], v[212:219], v[46:49]
	v_mfma_f32_16x16x128_f8f6f4 v[42:45], v[10:17], v[212:219], v[42:45]
	v_mfma_f32_16x16x128_f8f6f4 v[86:89], v[18:25], v[188:195], v[86:89]
	v_mfma_f32_16x16x128_f8f6f4 v[82:85], v[26:33], v[188:195], v[82:85]
	v_mfma_f32_16x16x128_f8f6f4 v[70:73], v[18:25], v[196:203], v[70:73]
	v_mfma_f32_16x16x128_f8f6f4 v[66:69], v[26:33], v[196:203], v[66:69]
	v_mfma_f32_16x16x128_f8f6f4 v[54:57], v[18:25], v[204:211], v[54:57]
	v_mfma_f32_16x16x128_f8f6f4 v[50:53], v[26:33], v[204:211], v[50:53]
	v_mfma_f32_16x16x128_f8f6f4 v[38:41], v[18:25], v[212:219], v[38:41]
	v_mfma_f32_16x16x128_f8f6f4 v[34:37], v[26:33], v[212:219], v[34:37]
	s_waitcnt vmcnt(8)
	s_barrier
	s_add_i32 s53, s53, 2
	s_add_u32 s28, s28, 0x100
	s_addc_u32 s29, s29, 0
	s_add_u32 s51, s51, 0x100
	s_addc_u32 s52, s52, 0
	s_cmp_gt_u32 s53, 13
	s_cbranch_scc0 .LBB0_839
	s_and_b64 vcc, exec, s[10:11]
	s_cbranch_vccz .LBB0_842
	s_barrier

.LBB0_863:
	ds_read_b128 v[146:149], v154
	ds_read_b128 v[158:161], v154 offset:1024
	ds_read_b128 v[162:165], v154 offset:2048
	ds_read_b128 v[166:169], v154 offset:3072
	ds_read_b128 v[170:173], v155
	ds_read_b128 v[174:177], v155 offset:1024
	ds_read_b128 v[178:181], v155 offset:2048
	ds_read_b128 v[182:185], v155 offset:3072
	s_add_u32 s22, s20, 0xfff80080
	s_addc_u32 s23, s21, -1
	s_cmp_eq_u32 s43, 28
	s_cselect_b32 s25, s13, s23
	s_cselect_b32 s24, s39, s22
	s_cselect_b32 s23, s11, s42
	s_cselect_b32 s22, s40, s41
	s_add_i32 m0, s19, 0xc000
	ds_read_b128 v[186:189], v156
	ds_read_b128 v[190:193], v156 offset:1024
	ds_read_b128 v[194:197], v156 offset:2048
	ds_read_b128 v[198:201], v156 offset:3072
	ds_read_b128 v[202:205], v156 offset:4096
	ds_read_b128 v[206:209], v156 offset:5120
	ds_read_b128 v[210:213], v156 offset:6144
	ds_read_b128 v[214:217], v156 offset:7168
	global_load_lds_dwordx4 v138, s[20:21]
	s_add_i32 m0, s19, 0xe000
	s_nop 0
	global_load_lds_dwordx4 v140, s[20:21]
	s_waitcnt lgkmcnt(0)
	s_barrier
	v_mfma_f32_16x16x32_bf16 v[126:129], v[146:149], v[186:189], v[126:129]
	v_mfma_f32_16x16x32_bf16 v[126:129], v[158:161], v[190:193], v[126:129]
	v_mfma_f32_16x16x32_bf16 v[122:125], v[162:165], v[186:189], v[122:125]
	v_mfma_f32_16x16x32_bf16 v[122:125], v[166:169], v[190:193], v[122:125]
	v_mfma_f32_16x16x32_bf16 v[110:113], v[146:149], v[194:197], v[110:113]
	v_mfma_f32_16x16x32_bf16 v[110:113], v[158:161], v[198:201], v[110:113]
	v_mfma_f32_16x16x32_bf16 v[106:109], v[162:165], v[194:197], v[106:109]
	v_mfma_f32_16x16x32_bf16 v[106:109], v[166:169], v[198:201], v[106:109]
	v_mfma_f32_16x16x32_bf16 v[94:97], v[146:149], v[202:205], v[94:97]
	v_mfma_f32_16x16x32_bf16 v[94:97], v[158:161], v[206:209], v[94:97]
	v_mfma_f32_16x16x32_bf16 v[90:93], v[162:165], v[202:205], v[90:93]
	v_mfma_f32_16x16x32_bf16 v[90:93], v[166:169], v[206:209], v[90:93]
	v_mfma_f32_16x16x32_bf16 v[78:81], v[146:149], v[210:213], v[78:81]
	v_mfma_f32_16x16x32_bf16 v[78:81], v[158:161], v[214:217], v[78:81]
	v_mfma_f32_16x16x32_bf16 v[74:77], v[162:165], v[210:213], v[74:77]
	v_mfma_f32_16x16x32_bf16 v[74:77], v[166:169], v[214:217], v[74:77]
	v_mfma_f32_16x16x32_bf16 v[118:121], v[170:173], v[186:189], v[118:121]
	v_mfma_f32_16x16x32_bf16 v[118:121], v[174:177], v[190:193], v[118:121]
	v_mfma_f32_16x16x32_bf16 v[114:117], v[178:181], v[186:189], v[114:117]
	v_mfma_f32_16x16x32_bf16 v[114:117], v[182:185], v[190:193], v[114:117]
	v_mfma_f32_16x16x32_bf16 v[102:105], v[170:173], v[194:197], v[102:105]
	v_mfma_f32_16x16x32_bf16 v[102:105], v[174:177], v[198:201], v[102:105]
	v_mfma_f32_16x16x32_bf16 v[98:101], v[178:181], v[194:197], v[98:101]
	v_mfma_f32_16x16x32_bf16 v[98:101], v[182:185], v[198:201], v[98:101]
	v_mfma_f32_16x16x32_bf16 v[86:89], v[170:173], v[202:205], v[86:89]
	v_mfma_f32_16x16x32_bf16 v[86:89], v[174:177], v[206:209], v[86:89]
	v_mfma_f32_16x16x32_bf16 v[82:85], v[178:181], v[202:205], v[82:85]
	v_mfma_f32_16x16x32_bf16 v[82:85], v[182:185], v[206:209], v[82:85]
	v_mfma_f32_16x16x32_bf16 v[70:73], v[170:173], v[210:213], v[70:73]
	v_mfma_f32_16x16x32_bf16 v[70:73], v[174:177], v[214:217], v[70:73]
	v_mfma_f32_16x16x32_bf16 v[66:69], v[178:181], v[210:213], v[66:69]
	v_mfma_f32_16x16x32_bf16 v[66:69], v[182:185], v[214:217], v[66:69]
	s_waitcnt vmcnt(8)
	s_barrier
	s_add_i32 s44, s36, s27
	s_mov_b32 m0, s44
	ds_read_b128 v[186:189], v156 offset:16384
	ds_read_b128 v[190:193], v156 offset:17408
	ds_read_b128 v[194:197], v156 offset:18432
	ds_read_b128 v[198:201], v156 offset:19456
	ds_read_b128 v[202:205], v156 offset:20480
	ds_read_b128 v[206:209], v156 offset:21504
	ds_read_b128 v[210:213], v156 offset:22528
	ds_read_b128 v[214:217], v156 offset:23552
	global_load_lds_dwordx4 v132, s[22:23]
	s_add_i32 m0, s44, 0x2000
	s_add_u32 s44, s22, 0x80000
	s_addc_u32 s45, s23, 0
	s_add_i32 s46, s37, s27
	global_load_lds_dwordx4 v136, s[22:23]
	s_mov_b32 m0, s46
	global_load_lds_dwordx4 v132, s[44:45]
	s_add_i32 m0, s46, 0x2000
	s_nop 0
	global_load_lds_dwordx4 v136, s[44:45]
	s_mov_b32 m0, s19
	s_nop 0
	global_load_lds_dwordx4 v130, s[24:25]
	s_mov_b32 m0, s28
	s_nop 0
	global_load_lds_dwordx4 v134, s[24:25]
	s_waitcnt lgkmcnt(0)
	s_barrier
	v_mfma_f32_16x16x32_bf16 v[62:65], v[146:149], v[186:189], v[62:65]
	v_mfma_f32_16x16x32_bf16 v[62:65], v[158:161], v[190:193], v[62:65]
	v_mfma_f32_16x16x32_bf16 v[58:61], v[162:165], v[186:189], v[58:61]
	v_mfma_f32_16x16x32_bf16 v[58:61], v[166:169], v[190:193], v[58:61]
	v_mfma_f32_16x16x32_bf16 v[46:49], v[146:149], v[194:197], v[46:49]
	v_mfma_f32_16x16x32_bf16 v[46:49], v[158:161], v[198:201], v[46:49]
	v_mfma_f32_16x16x32_bf16 v[42:45], v[162:165], v[194:197], v[42:45]
	v_mfma_f32_16x16x32_bf16 v[42:45], v[166:169], v[198:201], v[42:45]
	v_mfma_f32_16x16x32_bf16 v[30:33], v[146:149], v[202:205], v[30:33]
	v_mfma_f32_16x16x32_bf16 v[30:33], v[158:161], v[206:209], v[30:33]
	v_mfma_f32_16x16x32_bf16 v[26:29], v[162:165], v[202:205], v[26:29]
	v_mfma_f32_16x16x32_bf16 v[26:29], v[166:169], v[206:209], v[26:29]
	v_mfma_f32_16x16x32_bf16 v[14:17], v[146:149], v[210:213], v[14:17]
	v_mfma_f32_16x16x32_bf16 v[14:17], v[158:161], v[214:217], v[14:17]
	v_mfma_f32_16x16x32_bf16 v[10:13], v[162:165], v[210:213], v[10:13]
	v_mfma_f32_16x16x32_bf16 v[10:13], v[166:169], v[214:217], v[10:13]
	v_mfma_f32_16x16x32_bf16 v[54:57], v[170:173], v[186:189], v[54:57]
	v_mfma_f32_16x16x32_bf16 v[54:57], v[174:177], v[190:193], v[54:57]
	v_mfma_f32_16x16x32_bf16 v[50:53], v[178:181], v[186:189], v[50:53]
	v_mfma_f32_16x16x32_bf16 v[50:53], v[182:185], v[190:193], v[50:53]
	v_mfma_f32_16x16x32_bf16 v[38:41], v[170:173], v[194:197], v[38:41]
	v_mfma_f32_16x16x32_bf16 v[38:41], v[174:177], v[198:201], v[38:41]
	v_mfma_f32_16x16x32_bf16 v[34:37], v[178:181], v[194:197], v[34:37]
	v_mfma_f32_16x16x32_bf16 v[34:37], v[182:185], v[198:201], v[34:37]
	v_mfma_f32_16x16x32_bf16 v[22:25], v[170:173], v[202:205], v[22:25]
	v_mfma_f32_16x16x32_bf16 v[22:25], v[174:177], v[206:209], v[22:25]
	v_mfma_f32_16x16x32_bf16 v[18:21], v[178:181], v[202:205], v[18:21]
	v_mfma_f32_16x16x32_bf16 v[18:21], v[182:185], v[206:209], v[18:21]
	v_mfma_f32_16x16x32_bf16 v[6:9], v[170:173], v[210:213], v[6:9]
	v_mfma_f32_16x16x32_bf16 v[6:9], v[174:177], v[214:217], v[6:9]
	v_mfma_f32_16x16x32_bf16 v[2:5], v[178:181], v[210:213], v[2:5]
	v_mfma_f32_16x16x32_bf16 v[2:5], v[182:185], v[214:217], v[2:5]
	s_waitcnt vmcnt(8)
	s_barrier
	s_add_i32 s44, 0, 0x18000
	s_add_i32 s45, 0, 0x1c000
	ds_read_b128 v[146:149], v246
	ds_read_b128 v[158:161], v246 offset:1024
	ds_read_b128 v[162:165], v246 offset:2048
	ds_read_b128 v[166:169], v246 offset:3072
	ds_read_b128 v[170:173], v247
	ds_read_b128 v[174:177], v247 offset:1024
	ds_read_b128 v[178:181], v247 offset:2048
	ds_read_b128 v[182:185], v247 offset:3072
	s_add_u32 s98, s24, 0x80
	s_addc_u32 s99, s25, 0
	s_add_u32 s24, s24, 0x80000
	s_addc_u32 s25, s25, 0
	s_mov_b32 m0, s29
	ds_read_b128 v[186:189], v156 offset:32768
	ds_read_b128 v[190:193], v156 offset:33792
	ds_read_b128 v[194:197], v156 offset:34816
	ds_read_b128 v[198:201], v156 offset:35840
	ds_read_b128 v[202:205], v156 offset:36864
	ds_read_b128 v[206:209], v156 offset:37888
	ds_read_b128 v[210:213], v156 offset:38912
	ds_read_b128 v[214:217], v156 offset:39936
	global_load_lds_dwordx4 v130, s[24:25]
	s_mov_b32 m0, s30
	s_nop 0
	global_load_lds_dwordx4 v134, s[24:25]
	s_waitcnt lgkmcnt(0)
	s_barrier
	v_mfma_f32_16x16x32_bf16 v[126:129], v[146:149], v[186:189], v[126:129]
	v_mfma_f32_16x16x32_bf16 v[126:129], v[158:161], v[190:193], v[126:129]
	v_mfma_f32_16x16x32_bf16 v[122:125], v[162:165], v[186:189], v[122:125]
	v_mfma_f32_16x16x32_bf16 v[122:125], v[166:169], v[190:193], v[122:125]
	v_mfma_f32_16x16x32_bf16 v[110:113], v[146:149], v[194:197], v[110:113]
	v_mfma_f32_16x16x32_bf16 v[110:113], v[158:161], v[198:201], v[110:113]
	v_mfma_f32_16x16x32_bf16 v[106:109], v[162:165], v[194:197], v[106:109]
	v_mfma_f32_16x16x32_bf16 v[106:109], v[166:169], v[198:201], v[106:109]
	v_mfma_f32_16x16x32_bf16 v[94:97], v[146:149], v[202:205], v[94:97]
	v_mfma_f32_16x16x32_bf16 v[94:97], v[158:161], v[206:209], v[94:97]
	v_mfma_f32_16x16x32_bf16 v[90:93], v[162:165], v[202:205], v[90:93]
	v_mfma_f32_16x16x32_bf16 v[90:93], v[166:169], v[206:209], v[90:93]
	v_mfma_f32_16x16x32_bf16 v[78:81], v[146:149], v[210:213], v[78:81]
	v_mfma_f32_16x16x32_bf16 v[78:81], v[158:161], v[214:217], v[78:81]
	v_mfma_f32_16x16x32_bf16 v[74:77], v[162:165], v[210:213], v[74:77]
	v_mfma_f32_16x16x32_bf16 v[74:77], v[166:169], v[214:217], v[74:77]
	v_mfma_f32_16x16x32_bf16 v[118:121], v[170:173], v[186:189], v[118:121]
	v_mfma_f32_16x16x32_bf16 v[118:121], v[174:177], v[190:193], v[118:121]
	v_mfma_f32_16x16x32_bf16 v[114:117], v[178:181], v[186:189], v[114:117]
	v_mfma_f32_16x16x32_bf16 v[114:117], v[182:185], v[190:193], v[114:117]
	v_mfma_f32_16x16x32_bf16 v[102:105], v[170:173], v[194:197], v[102:105]
	v_mfma_f32_16x16x32_bf16 v[102:105], v[174:177], v[198:201], v[102:105]
	v_mfma_f32_16x16x32_bf16 v[98:101], v[178:181], v[194:197], v[98:101]
	v_mfma_f32_16x16x32_bf16 v[98:101], v[182:185], v[198:201], v[98:101]
	v_mfma_f32_16x16x32_bf16 v[86:89], v[170:173], v[202:205], v[86:89]
	v_mfma_f32_16x16x32_bf16 v[86:89], v[174:177], v[206:209], v[86:89]
	v_mfma_f32_16x16x32_bf16 v[82:85], v[178:181], v[202:205], v[82:85]
	v_mfma_f32_16x16x32_bf16 v[82:85], v[182:185], v[206:209], v[82:85]
	v_mfma_f32_16x16x32_bf16 v[70:73], v[170:173], v[210:213], v[70:73]
	v_mfma_f32_16x16x32_bf16 v[70:73], v[174:177], v[214:217], v[70:73]
	v_mfma_f32_16x16x32_bf16 v[66:69], v[178:181], v[210:213], v[66:69]
	v_mfma_f32_16x16x32_bf16 v[66:69], v[182:185], v[214:217], v[66:69]
	s_waitcnt vmcnt(8)
	s_barrier
	s_add_i32 s24, s44, s27
	s_mov_b32 m0, s24
	ds_read_b128 v[186:189], v156 offset:49152
	ds_read_b128 v[190:193], v156 offset:50176
	ds_read_b128 v[194:197], v156 offset:51200
	ds_read_b128 v[198:201], v156 offset:52224
	ds_read_b128 v[202:205], v156 offset:53248
	ds_read_b128 v[206:209], v156 offset:54272
	ds_read_b128 v[210:213], v156 offset:55296
	ds_read_b128 v[214:217], v156 offset:56320
	s_add_u32 s22, s22, 0x80
	s_addc_u32 s23, s23, 0
	global_load_lds_dwordx4 v132, s[22:23]
	s_add_i32 m0, s24, 0x2000
	s_add_i32 s24, s45, s27
	global_load_lds_dwordx4 v136, s[22:23]
	s_add_u32 s22, s22, 0x80000
	s_addc_u32 s23, s23, 0
	s_mov_b32 m0, s24
	s_nop 0
	global_load_lds_dwordx4 v132, s[22:23]
	s_add_i32 m0, s24, 0x2000
	s_nop 0
	global_load_lds_dwordx4 v136, s[22:23]
	s_mov_b32 m0, s33
	s_nop 0
	global_load_lds_dwordx4 v130, s[98:99]
	s_mov_b32 m0, s34
	s_nop 0
	global_load_lds_dwordx4 v134, s[98:99]
	s_waitcnt lgkmcnt(0)
	s_barrier
	v_mfma_f32_16x16x32_bf16 v[62:65], v[146:149], v[186:189], v[62:65]
	v_mfma_f32_16x16x32_bf16 v[62:65], v[158:161], v[190:193], v[62:65]
	v_mfma_f32_16x16x32_bf16 v[58:61], v[162:165], v[186:189], v[58:61]
	v_mfma_f32_16x16x32_bf16 v[58:61], v[166:169], v[190:193], v[58:61]
	v_mfma_f32_16x16x32_bf16 v[46:49], v[146:149], v[194:197], v[46:49]
	v_mfma_f32_16x16x32_bf16 v[46:49], v[158:161], v[198:201], v[46:49]
	v_mfma_f32_16x16x32_bf16 v[42:45], v[162:165], v[194:197], v[42:45]
	v_mfma_f32_16x16x32_bf16 v[42:45], v[166:169], v[198:201], v[42:45]
	v_mfma_f32_16x16x32_bf16 v[30:33], v[146:149], v[202:205], v[30:33]
	v_mfma_f32_16x16x32_bf16 v[30:33], v[158:161], v[206:209], v[30:33]
	v_mfma_f32_16x16x32_bf16 v[26:29], v[162:165], v[202:205], v[26:29]
	v_mfma_f32_16x16x32_bf16 v[26:29], v[166:169], v[206:209], v[26:29]
	v_mfma_f32_16x16x32_bf16 v[14:17], v[146:149], v[210:213], v[14:17]
	v_mfma_f32_16x16x32_bf16 v[14:17], v[158:161], v[214:217], v[14:17]
	v_mfma_f32_16x16x32_bf16 v[10:13], v[162:165], v[210:213], v[10:13]
	v_mfma_f32_16x16x32_bf16 v[10:13], v[166:169], v[214:217], v[10:13]
	v_mfma_f32_16x16x32_bf16 v[54:57], v[170:173], v[186:189], v[54:57]
	v_mfma_f32_16x16x32_bf16 v[54:57], v[174:177], v[190:193], v[54:57]
	v_mfma_f32_16x16x32_bf16 v[50:53], v[178:181], v[186:189], v[50:53]
	v_mfma_f32_16x16x32_bf16 v[50:53], v[182:185], v[190:193], v[50:53]
	v_mfma_f32_16x16x32_bf16 v[38:41], v[170:173], v[194:197], v[38:41]
	v_mfma_f32_16x16x32_bf16 v[38:41], v[174:177], v[198:201], v[38:41]
	v_mfma_f32_16x16x32_bf16 v[34:37], v[178:181], v[194:197], v[34:37]
	v_mfma_f32_16x16x32_bf16 v[34:37], v[182:185], v[198:201], v[34:37]
	v_mfma_f32_16x16x32_bf16 v[22:25], v[170:173], v[202:205], v[22:25]
	v_mfma_f32_16x16x32_bf16 v[22:25], v[174:177], v[206:209], v[22:25]
	v_mfma_f32_16x16x32_bf16 v[18:21], v[178:181], v[202:205], v[18:21]
	v_mfma_f32_16x16x32_bf16 v[18:21], v[182:185], v[206:209], v[18:21]
	v_mfma_f32_16x16x32_bf16 v[6:9], v[170:173], v[210:213], v[6:9]
	v_mfma_f32_16x16x32_bf16 v[6:9], v[174:177], v[214:217], v[6:9]
	v_mfma_f32_16x16x32_bf16 v[2:5], v[178:181], v[210:213], v[2:5]
	v_mfma_f32_16x16x32_bf16 v[2:5], v[182:185], v[214:217], v[2:5]
	s_waitcnt vmcnt(8)
	s_barrier
	s_add_i32 s43, s43, 2
	s_add_u32 s20, s20, 0x100
	s_addc_u32 s21, s21, 0
	s_add_u32 s41, s41, 0x100
	s_addc_u32 s42, s42, 0
	s_cmp_gt_u32 s43, 29
	s_cbranch_scc0 .LBB0_863
	s_and_b64 vcc, exec, s[8:9]
	s_cbranch_vccz .LBB0_866
	s_barrier

.LBB0_941:
	ds_read_b128 v[90:93], v188
	ds_read_b128 v[94:97], v188 offset:1024
	ds_read_b128 v[102:105], v188 offset:2048
	ds_read_b128 v[110:113], v188 offset:3072
	ds_read_b128 v[146:149], v189
	ds_read_b128 v[150:153], v189 offset:1024
	ds_read_b128 v[154:157], v189 offset:2048
	ds_read_b128 v[158:161], v189 offset:3072
	s_add_u32 s30, s28, 0xfff00080
	s_addc_u32 s31, s29, -1
	s_cmp_eq_u32 s51, 60
	s_cselect_b32 s35, s21, s31
	s_cselect_b32 s34, s27, s30
	s_cselect_b32 s31, s19, s50
	s_cselect_b32 s30, s48, s49
	s_add_i32 m0, s36, 0xc000
	ds_read_b128 v[178:181], v190
	ds_read_b128 v[182:185], v190 offset:1024
	ds_read_b128 v[192:195], v190 offset:2048
	ds_read_b128 v[196:199], v190 offset:3072
	ds_read_b128 v[200:203], v190 offset:4096
	ds_read_b128 v[204:207], v190 offset:5120
	ds_read_b128 v[208:211], v190 offset:6144
	ds_read_b128 v[212:215], v190 offset:7168
	global_load_lds_dwordx4 v170, s[28:29]
	s_add_i32 m0, s36, 0xe000
	s_nop 0
	global_load_lds_dwordx4 v172, s[28:29]
	s_waitcnt lgkmcnt(0)
	s_barrier
	v_mfma_f32_16x16x32_bf16 v[142:145], v[90:93], v[178:181], v[142:145]
	v_mfma_f32_16x16x32_bf16 v[142:145], v[94:97], v[182:185], v[142:145]
	v_mfma_f32_16x16x32_bf16 v[138:141], v[102:105], v[178:181], v[138:141]
	v_mfma_f32_16x16x32_bf16 v[138:141], v[110:113], v[182:185], v[138:141]
	v_mfma_f32_16x16x32_bf16 v[126:129], v[90:93], v[192:195], v[126:129]
	v_mfma_f32_16x16x32_bf16 v[126:129], v[94:97], v[196:199], v[126:129]
	v_mfma_f32_16x16x32_bf16 v[122:125], v[102:105], v[192:195], v[122:125]
	v_mfma_f32_16x16x32_bf16 v[122:125], v[110:113], v[196:199], v[122:125]
	v_mfma_f32_16x16x32_bf16 v[106:109], v[90:93], v[200:203], v[106:109]
	v_mfma_f32_16x16x32_bf16 v[106:109], v[94:97], v[204:207], v[106:109]
	v_mfma_f32_16x16x32_bf16 v[98:101], v[102:105], v[200:203], v[98:101]
	v_mfma_f32_16x16x32_bf16 v[98:101], v[110:113], v[204:207], v[98:101]
	v_mfma_f32_16x16x32_bf16 v[78:81], v[90:93], v[208:211], v[78:81]
	v_mfma_f32_16x16x32_bf16 v[78:81], v[94:97], v[212:215], v[78:81]
	v_mfma_f32_16x16x32_bf16 v[74:77], v[102:105], v[208:211], v[74:77]
	v_mfma_f32_16x16x32_bf16 v[74:77], v[110:113], v[212:215], v[74:77]
	v_mfma_f32_16x16x32_bf16 v[134:137], v[146:149], v[178:181], v[134:137]
	v_mfma_f32_16x16x32_bf16 v[134:137], v[150:153], v[182:185], v[134:137]
	v_mfma_f32_16x16x32_bf16 v[130:133], v[154:157], v[178:181], v[130:133]
	v_mfma_f32_16x16x32_bf16 v[130:133], v[158:161], v[182:185], v[130:133]
	v_mfma_f32_16x16x32_bf16 v[118:121], v[146:149], v[192:195], v[118:121]
	v_mfma_f32_16x16x32_bf16 v[118:121], v[150:153], v[196:199], v[118:121]
	v_mfma_f32_16x16x32_bf16 v[114:117], v[154:157], v[192:195], v[114:117]
	v_mfma_f32_16x16x32_bf16 v[114:117], v[158:161], v[196:199], v[114:117]
	v_mfma_f32_16x16x32_bf16 v[86:89], v[146:149], v[200:203], v[86:89]
	v_mfma_f32_16x16x32_bf16 v[86:89], v[150:153], v[204:207], v[86:89]
	v_mfma_f32_16x16x32_bf16 v[82:85], v[154:157], v[200:203], v[82:85]
	v_mfma_f32_16x16x32_bf16 v[82:85], v[158:161], v[204:207], v[82:85]
	v_mfma_f32_16x16x32_bf16 v[70:73], v[146:149], v[208:211], v[70:73]
	v_mfma_f32_16x16x32_bf16 v[70:73], v[150:153], v[212:215], v[70:73]
	v_mfma_f32_16x16x32_bf16 v[66:69], v[154:157], v[208:211], v[66:69]
	v_mfma_f32_16x16x32_bf16 v[66:69], v[158:161], v[212:215], v[66:69]
	s_waitcnt vmcnt(8)
	s_barrier
	s_add_i32 s52, s45, s33
	s_mov_b32 m0, s52
	ds_read_b128 v[178:181], v190 offset:16384
	ds_read_b128 v[182:185], v190 offset:17408
	ds_read_b128 v[192:195], v190 offset:18432
	ds_read_b128 v[196:199], v190 offset:19456
	ds_read_b128 v[200:203], v190 offset:20480
	ds_read_b128 v[204:207], v190 offset:21504
	ds_read_b128 v[208:211], v190 offset:22528
	ds_read_b128 v[212:215], v190 offset:23552
	global_load_lds_dwordx4 v164, s[30:31]
	s_add_i32 m0, s52, 0x2000
	s_add_u32 s52, s30, 0x100000
	s_addc_u32 s53, s31, 0
	s_add_i32 s54, s46, s33
	global_load_lds_dwordx4 v168, s[30:31]
	s_mov_b32 m0, s54
	global_load_lds_dwordx4 v164, s[52:53]
	s_add_i32 m0, s54, 0x2000
	s_nop 0
	global_load_lds_dwordx4 v168, s[52:53]
	s_mov_b32 m0, s36
	s_nop 0
	global_load_lds_dwordx4 v162, s[34:35]
	s_mov_b32 m0, s37
	s_nop 0
	global_load_lds_dwordx4 v166, s[34:35]
	s_waitcnt lgkmcnt(0)
	s_barrier
	v_mfma_f32_16x16x32_bf16 v[62:65], v[90:93], v[178:181], v[62:65]
	v_mfma_f32_16x16x32_bf16 v[62:65], v[94:97], v[182:185], v[62:65]
	v_mfma_f32_16x16x32_bf16 v[58:61], v[102:105], v[178:181], v[58:61]
	v_mfma_f32_16x16x32_bf16 v[58:61], v[110:113], v[182:185], v[58:61]
	v_mfma_f32_16x16x32_bf16 v[46:49], v[90:93], v[192:195], v[46:49]
	v_mfma_f32_16x16x32_bf16 v[46:49], v[94:97], v[196:199], v[46:49]
	v_mfma_f32_16x16x32_bf16 v[42:45], v[102:105], v[192:195], v[42:45]
	v_mfma_f32_16x16x32_bf16 v[42:45], v[110:113], v[196:199], v[42:45]
	v_mfma_f32_16x16x32_bf16 v[30:33], v[90:93], v[200:203], v[30:33]
	v_mfma_f32_16x16x32_bf16 v[30:33], v[94:97], v[204:207], v[30:33]
	v_mfma_f32_16x16x32_bf16 v[26:29], v[102:105], v[200:203], v[26:29]
	v_mfma_f32_16x16x32_bf16 v[26:29], v[110:113], v[204:207], v[26:29]
	v_mfma_f32_16x16x32_bf16 v[14:17], v[90:93], v[208:211], v[14:17]
	v_mfma_f32_16x16x32_bf16 v[14:17], v[94:97], v[212:215], v[14:17]
	v_mfma_f32_16x16x32_bf16 v[10:13], v[102:105], v[208:211], v[10:13]
	v_mfma_f32_16x16x32_bf16 v[10:13], v[110:113], v[212:215], v[10:13]
	v_mfma_f32_16x16x32_bf16 v[54:57], v[146:149], v[178:181], v[54:57]
	v_mfma_f32_16x16x32_bf16 v[54:57], v[150:153], v[182:185], v[54:57]
	v_mfma_f32_16x16x32_bf16 v[50:53], v[154:157], v[178:181], v[50:53]
	v_mfma_f32_16x16x32_bf16 v[50:53], v[158:161], v[182:185], v[50:53]
	v_mfma_f32_16x16x32_bf16 v[38:41], v[146:149], v[192:195], v[38:41]
	v_mfma_f32_16x16x32_bf16 v[38:41], v[150:153], v[196:199], v[38:41]
	v_mfma_f32_16x16x32_bf16 v[34:37], v[154:157], v[192:195], v[34:37]
	v_mfma_f32_16x16x32_bf16 v[34:37], v[158:161], v[196:199], v[34:37]
	v_mfma_f32_16x16x32_bf16 v[22:25], v[146:149], v[200:203], v[22:25]
	v_mfma_f32_16x16x32_bf16 v[22:25], v[150:153], v[204:207], v[22:25]
	v_mfma_f32_16x16x32_bf16 v[18:21], v[154:157], v[200:203], v[18:21]
	v_mfma_f32_16x16x32_bf16 v[18:21], v[158:161], v[204:207], v[18:21]
	v_mfma_f32_16x16x32_bf16 v[6:9], v[146:149], v[208:211], v[6:9]
	v_mfma_f32_16x16x32_bf16 v[6:9], v[150:153], v[212:215], v[6:9]
	v_mfma_f32_16x16x32_bf16 v[2:5], v[154:157], v[208:211], v[2:5]
	v_mfma_f32_16x16x32_bf16 v[2:5], v[158:161], v[212:215], v[2:5]
	s_waitcnt vmcnt(8)
	s_barrier
	s_add_i32 s52, 0, 0x18000
	s_add_i32 s53, 0, 0x1c000
	ds_read_b128 v[90:93], v246
	ds_read_b128 v[94:97], v246 offset:1024
	ds_read_b128 v[102:105], v246 offset:2048
	ds_read_b128 v[110:113], v246 offset:3072
	ds_read_b128 v[146:149], v247
	ds_read_b128 v[150:153], v247 offset:1024
	ds_read_b128 v[154:157], v247 offset:2048
	ds_read_b128 v[158:161], v247 offset:3072
	s_add_u32 s98, s34, 0x80
	s_addc_u32 s99, s35, 0
	s_add_u32 s34, s34, 0x100000
	s_addc_u32 s35, s35, 0
	s_mov_b32 m0, s38
	ds_read_b128 v[178:181], v190 offset:32768
	ds_read_b128 v[182:185], v190 offset:33792
	ds_read_b128 v[192:195], v190 offset:34816
	ds_read_b128 v[196:199], v190 offset:35840
	ds_read_b128 v[200:203], v190 offset:36864
	ds_read_b128 v[204:207], v190 offset:37888
	ds_read_b128 v[208:211], v190 offset:38912
	ds_read_b128 v[212:215], v190 offset:39936
	global_load_lds_dwordx4 v162, s[34:35]
	s_mov_b32 m0, s39
	s_nop 0
	global_load_lds_dwordx4 v166, s[34:35]
	s_waitcnt lgkmcnt(0)
	s_barrier
	v_mfma_f32_16x16x32_bf16 v[142:145], v[90:93], v[178:181], v[142:145]
	v_mfma_f32_16x16x32_bf16 v[142:145], v[94:97], v[182:185], v[142:145]
	v_mfma_f32_16x16x32_bf16 v[138:141], v[102:105], v[178:181], v[138:141]
	v_mfma_f32_16x16x32_bf16 v[138:141], v[110:113], v[182:185], v[138:141]
	v_mfma_f32_16x16x32_bf16 v[126:129], v[90:93], v[192:195], v[126:129]
	v_mfma_f32_16x16x32_bf16 v[126:129], v[94:97], v[196:199], v[126:129]
	v_mfma_f32_16x16x32_bf16 v[122:125], v[102:105], v[192:195], v[122:125]
	v_mfma_f32_16x16x32_bf16 v[122:125], v[110:113], v[196:199], v[122:125]
	v_mfma_f32_16x16x32_bf16 v[106:109], v[90:93], v[200:203], v[106:109]
	v_mfma_f32_16x16x32_bf16 v[106:109], v[94:97], v[204:207], v[106:109]
	v_mfma_f32_16x16x32_bf16 v[98:101], v[102:105], v[200:203], v[98:101]
	v_mfma_f32_16x16x32_bf16 v[98:101], v[110:113], v[204:207], v[98:101]
	v_mfma_f32_16x16x32_bf16 v[78:81], v[90:93], v[208:211], v[78:81]
	v_mfma_f32_16x16x32_bf16 v[78:81], v[94:97], v[212:215], v[78:81]
	v_mfma_f32_16x16x32_bf16 v[74:77], v[102:105], v[208:211], v[74:77]
	v_mfma_f32_16x16x32_bf16 v[74:77], v[110:113], v[212:215], v[74:77]
	v_mfma_f32_16x16x32_bf16 v[134:137], v[146:149], v[178:181], v[134:137]
	v_mfma_f32_16x16x32_bf16 v[134:137], v[150:153], v[182:185], v[134:137]
	v_mfma_f32_16x16x32_bf16 v[130:133], v[154:157], v[178:181], v[130:133]
	v_mfma_f32_16x16x32_bf16 v[130:133], v[158:161], v[182:185], v[130:133]
	v_mfma_f32_16x16x32_bf16 v[118:121], v[146:149], v[192:195], v[118:121]
	v_mfma_f32_16x16x32_bf16 v[118:121], v[150:153], v[196:199], v[118:121]
	v_mfma_f32_16x16x32_bf16 v[114:117], v[154:157], v[192:195], v[114:117]
	v_mfma_f32_16x16x32_bf16 v[114:117], v[158:161], v[196:199], v[114:117]
	v_mfma_f32_16x16x32_bf16 v[86:89], v[146:149], v[200:203], v[86:89]
	v_mfma_f32_16x16x32_bf16 v[86:89], v[150:153], v[204:207], v[86:89]
	v_mfma_f32_16x16x32_bf16 v[82:85], v[154:157], v[200:203], v[82:85]
	v_mfma_f32_16x16x32_bf16 v[82:85], v[158:161], v[204:207], v[82:85]
	v_mfma_f32_16x16x32_bf16 v[70:73], v[146:149], v[208:211], v[70:73]
	v_mfma_f32_16x16x32_bf16 v[70:73], v[150:153], v[212:215], v[70:73]
	v_mfma_f32_16x16x32_bf16 v[66:69], v[154:157], v[208:211], v[66:69]
	v_mfma_f32_16x16x32_bf16 v[66:69], v[158:161], v[212:215], v[66:69]
	s_waitcnt vmcnt(8)
	s_barrier
	s_add_i32 s34, s52, s33
	s_mov_b32 m0, s34
	ds_read_b128 v[178:181], v190 offset:49152
	ds_read_b128 v[182:185], v190 offset:50176
	ds_read_b128 v[192:195], v190 offset:51200
	ds_read_b128 v[196:199], v190 offset:52224
	ds_read_b128 v[200:203], v190 offset:53248
	ds_read_b128 v[204:207], v190 offset:54272
	ds_read_b128 v[208:211], v190 offset:55296
	ds_read_b128 v[212:215], v190 offset:56320
	s_add_u32 s30, s30, 0x80
	s_addc_u32 s31, s31, 0
	global_load_lds_dwordx4 v164, s[30:31]
	s_add_i32 m0, s34, 0x2000
	s_add_i32 s34, s53, s33
	global_load_lds_dwordx4 v168, s[30:31]
	s_add_u32 s30, s30, 0x100000
	s_addc_u32 s31, s31, 0
	s_mov_b32 m0, s34
	s_nop 0
	global_load_lds_dwordx4 v164, s[30:31]
	s_add_i32 m0, s34, 0x2000
	s_nop 0
	global_load_lds_dwordx4 v168, s[30:31]
	s_mov_b32 m0, s43
	s_nop 0
	global_load_lds_dwordx4 v162, s[98:99]
	s_mov_b32 m0, s44
	s_nop 0
	global_load_lds_dwordx4 v166, s[98:99]
	s_waitcnt lgkmcnt(0)
	s_barrier
	v_mfma_f32_16x16x32_bf16 v[62:65], v[90:93], v[178:181], v[62:65]
	v_mfma_f32_16x16x32_bf16 v[62:65], v[94:97], v[182:185], v[62:65]
	v_mfma_f32_16x16x32_bf16 v[58:61], v[102:105], v[178:181], v[58:61]
	v_mfma_f32_16x16x32_bf16 v[58:61], v[110:113], v[182:185], v[58:61]
	v_mfma_f32_16x16x32_bf16 v[46:49], v[90:93], v[192:195], v[46:49]
	v_mfma_f32_16x16x32_bf16 v[46:49], v[94:97], v[196:199], v[46:49]
	v_mfma_f32_16x16x32_bf16 v[42:45], v[102:105], v[192:195], v[42:45]
	v_mfma_f32_16x16x32_bf16 v[42:45], v[110:113], v[196:199], v[42:45]
	v_mfma_f32_16x16x32_bf16 v[30:33], v[90:93], v[200:203], v[30:33]
	v_mfma_f32_16x16x32_bf16 v[30:33], v[94:97], v[204:207], v[30:33]
	v_mfma_f32_16x16x32_bf16 v[26:29], v[102:105], v[200:203], v[26:29]
	v_mfma_f32_16x16x32_bf16 v[26:29], v[110:113], v[204:207], v[26:29]
	v_mfma_f32_16x16x32_bf16 v[14:17], v[90:93], v[208:211], v[14:17]
	v_mfma_f32_16x16x32_bf16 v[14:17], v[94:97], v[212:215], v[14:17]
	v_mfma_f32_16x16x32_bf16 v[10:13], v[102:105], v[208:211], v[10:13]
	v_mfma_f32_16x16x32_bf16 v[10:13], v[110:113], v[212:215], v[10:13]
	v_mfma_f32_16x16x32_bf16 v[54:57], v[146:149], v[178:181], v[54:57]
	v_mfma_f32_16x16x32_bf16 v[54:57], v[150:153], v[182:185], v[54:57]
	v_mfma_f32_16x16x32_bf16 v[50:53], v[154:157], v[178:181], v[50:53]
	v_mfma_f32_16x16x32_bf16 v[50:53], v[158:161], v[182:185], v[50:53]
	v_mfma_f32_16x16x32_bf16 v[38:41], v[146:149], v[192:195], v[38:41]
	v_mfma_f32_16x16x32_bf16 v[38:41], v[150:153], v[196:199], v[38:41]
	v_mfma_f32_16x16x32_bf16 v[34:37], v[154:157], v[192:195], v[34:37]
	v_mfma_f32_16x16x32_bf16 v[34:37], v[158:161], v[196:199], v[34:37]
	v_mfma_f32_16x16x32_bf16 v[22:25], v[146:149], v[200:203], v[22:25]
	v_mfma_f32_16x16x32_bf16 v[22:25], v[150:153], v[204:207], v[22:25]
	v_mfma_f32_16x16x32_bf16 v[18:21], v[154:157], v[200:203], v[18:21]
	v_mfma_f32_16x16x32_bf16 v[18:21], v[158:161], v[204:207], v[18:21]
	v_mfma_f32_16x16x32_bf16 v[6:9], v[146:149], v[208:211], v[6:9]
	v_mfma_f32_16x16x32_bf16 v[6:9], v[150:153], v[212:215], v[6:9]
	v_mfma_f32_16x16x32_bf16 v[2:5], v[154:157], v[208:211], v[2:5]
	v_mfma_f32_16x16x32_bf16 v[2:5], v[158:161], v[212:215], v[2:5]
	s_waitcnt vmcnt(8)
	s_barrier
	s_add_i32 s51, s51, 2
	s_add_u32 s28, s28, 0x100
	s_addc_u32 s29, s29, 0
	s_add_u32 s49, s49, 0x100
	s_addc_u32 s50, s50, 0
	s_cmp_gt_u32 s51, 61
	s_cbranch_scc0 .LBB0_941
	s_and_b64 vcc, exec, s[16:17]
	s_cbranch_vccz .LBB0_944
	s_barrier

.LBB0_1153:
	v_add_u32_e32 v146, s78, v187
	v_add_u32_e32 v162, s79, v187
	s_add_u32 s98, s46, s10
	s_addc_u32 s99, s47, s11
	s_add_u32 s98, s98, 0x100080
	s_addc_u32 s99, s99, 0
	s_add_u32 s56, s46, s10
	ds_read_b128 v[134:137], v146
	ds_read_b128 v[138:141], v146 offset:1024
	ds_read_b128 v[142:145], v146 offset:2048
	ds_read_b128 v[146:149], v146 offset:3072
	ds_read_b128 v[150:153], v162
	ds_read_b128 v[154:157], v162 offset:1024
	ds_read_b128 v[158:161], v162 offset:2048
	ds_read_b128 v[162:165], v162 offset:3072
	s_addc_u32 s57, s47, s11
	s_add_u32 s56, s56, 0x100
	s_addc_u32 s57, s57, 0
	s_add_u32 s84, s33, s10
	s_addc_u32 s85, s72, s11
	s_cmpk_eq_i32 s10, 0x1f00
	s_cselect_b32 s59, s29, s57
	s_cselect_b32 s58, s45, s56
	s_cselect_b32 s57, s43, s85
	s_cselect_b32 s56, s73, s84
	s_add_i32 m0, s64, 0xc000
	ds_read_b128 v[166:169], v230
	ds_read_b128 v[170:173], v230 offset:1024
	ds_read_b128 v[174:177], v230 offset:2048
	ds_read_b128 v[202:205], v230 offset:3072
	ds_read_b128 v[206:209], v230 offset:4096
	ds_read_b128 v[210:213], v230 offset:5120
	ds_read_b128 v[214:217], v230 offset:6144
	ds_read_b128 v[218:221], v230 offset:7168
	global_load_lds_dwordx4 v178, s[98:99]
	s_add_i32 m0, s64, 0xe000
	s_nop 0
	global_load_lds_dwordx4 v182, s[98:99]
	s_waitcnt lgkmcnt(0)
	s_barrier
	v_mfma_f32_16x16x32_bf16 v[2:5], v[134:137], v[166:169], v[2:5]
	v_mfma_f32_16x16x32_bf16 v[2:5], v[138:141], v[170:173], v[2:5]
	v_mfma_f32_16x16x32_bf16 v[126:129], v[142:145], v[166:169], v[126:129]
	v_mfma_f32_16x16x32_bf16 v[126:129], v[146:149], v[170:173], v[126:129]
	v_mfma_f32_16x16x32_bf16 v[122:125], v[134:137], v[174:177], v[122:125]
	v_mfma_f32_16x16x32_bf16 v[122:125], v[138:141], v[202:205], v[122:125]
	v_mfma_f32_16x16x32_bf16 v[118:121], v[142:145], v[174:177], v[118:121]
	v_mfma_f32_16x16x32_bf16 v[118:121], v[146:149], v[202:205], v[118:121]
	v_mfma_f32_16x16x32_bf16 v[114:117], v[134:137], v[206:209], v[114:117]
	v_mfma_f32_16x16x32_bf16 v[114:117], v[138:141], v[210:213], v[114:117]
	v_mfma_f32_16x16x32_bf16 v[110:113], v[142:145], v[206:209], v[110:113]
	v_mfma_f32_16x16x32_bf16 v[110:113], v[146:149], v[210:213], v[110:113]
	v_mfma_f32_16x16x32_bf16 v[106:109], v[134:137], v[214:217], v[106:109]
	v_mfma_f32_16x16x32_bf16 v[106:109], v[138:141], v[218:221], v[106:109]
	v_mfma_f32_16x16x32_bf16 v[102:105], v[142:145], v[214:217], v[102:105]
	v_mfma_f32_16x16x32_bf16 v[102:105], v[146:149], v[218:221], v[102:105]
	v_mfma_f32_16x16x32_bf16 v[98:101], v[150:153], v[166:169], v[98:101]
	v_mfma_f32_16x16x32_bf16 v[98:101], v[154:157], v[170:173], v[98:101]
	v_mfma_f32_16x16x32_bf16 v[94:97], v[158:161], v[166:169], v[94:97]
	v_mfma_f32_16x16x32_bf16 v[94:97], v[162:165], v[170:173], v[94:97]
	v_mfma_f32_16x16x32_bf16 v[90:93], v[150:153], v[174:177], v[90:93]
	v_mfma_f32_16x16x32_bf16 v[90:93], v[154:157], v[202:205], v[90:93]
	v_mfma_f32_16x16x32_bf16 v[86:89], v[158:161], v[174:177], v[86:89]
	v_mfma_f32_16x16x32_bf16 v[86:89], v[162:165], v[202:205], v[86:89]
	v_mfma_f32_16x16x32_bf16 v[82:85], v[150:153], v[206:209], v[82:85]
	v_mfma_f32_16x16x32_bf16 v[82:85], v[154:157], v[210:213], v[82:85]
	v_mfma_f32_16x16x32_bf16 v[78:81], v[158:161], v[206:209], v[78:81]
	v_mfma_f32_16x16x32_bf16 v[78:81], v[162:165], v[210:213], v[78:81]
	v_mfma_f32_16x16x32_bf16 v[74:77], v[150:153], v[214:217], v[74:77]
	v_mfma_f32_16x16x32_bf16 v[74:77], v[154:157], v[218:221], v[74:77]
	v_mfma_f32_16x16x32_bf16 v[70:73], v[158:161], v[214:217], v[70:73]
	v_mfma_f32_16x16x32_bf16 v[70:73], v[162:165], v[218:221], v[70:73]
	s_waitcnt vmcnt(8)
	s_barrier
	s_add_i32 s84, s78, s63
	s_mov_b32 m0, s84
	ds_read_b128 v[166:169], v230 offset:16384
	ds_read_b128 v[170:173], v230 offset:17408
	ds_read_b128 v[174:177], v230 offset:18432
	ds_read_b128 v[202:205], v230 offset:19456
	ds_read_b128 v[206:209], v230 offset:20480
	ds_read_b128 v[210:213], v230 offset:21504
	ds_read_b128 v[214:217], v230 offset:22528
	ds_read_b128 v[218:221], v230 offset:23552
	global_load_lds_dwordx4 v180, s[56:57]
	s_add_i32 m0, s84, 0x2000
	s_add_u32 s84, s56, 0x100000
	s_addc_u32 s85, s57, 0
	s_add_i32 s86, s79, s63
	global_load_lds_dwordx4 v184, s[56:57]
	s_mov_b32 m0, s86
	s_nop 0
	global_load_lds_dwordx4 v180, s[84:85]
	s_add_i32 m0, s86, 0x2000
	s_nop 0
	global_load_lds_dwordx4 v184, s[84:85]
	s_mov_b32 m0, s64
	s_nop 0
	global_load_lds_dwordx4 v178, s[58:59]
	s_mov_b32 m0, s65
	s_nop 0
	global_load_lds_dwordx4 v182, s[58:59]
	s_waitcnt lgkmcnt(0)
	s_barrier
	v_mfma_f32_16x16x32_bf16 v[66:69], v[134:137], v[166:169], v[66:69]
	v_mfma_f32_16x16x32_bf16 v[66:69], v[138:141], v[170:173], v[66:69]
	v_mfma_f32_16x16x32_bf16 v[62:65], v[142:145], v[166:169], v[62:65]
	v_mfma_f32_16x16x32_bf16 v[62:65], v[146:149], v[170:173], v[62:65]
	v_mfma_f32_16x16x32_bf16 v[58:61], v[134:137], v[174:177], v[58:61]
	v_mfma_f32_16x16x32_bf16 v[58:61], v[138:141], v[202:205], v[58:61]
	v_mfma_f32_16x16x32_bf16 v[54:57], v[142:145], v[174:177], v[54:57]
	v_mfma_f32_16x16x32_bf16 v[54:57], v[146:149], v[202:205], v[54:57]
	v_mfma_f32_16x16x32_bf16 v[50:53], v[134:137], v[206:209], v[50:53]
	v_mfma_f32_16x16x32_bf16 v[50:53], v[138:141], v[210:213], v[50:53]
	v_mfma_f32_16x16x32_bf16 v[46:49], v[142:145], v[206:209], v[46:49]
	v_mfma_f32_16x16x32_bf16 v[46:49], v[146:149], v[210:213], v[46:49]
	v_mfma_f32_16x16x32_bf16 v[42:45], v[134:137], v[214:217], v[42:45]
	v_mfma_f32_16x16x32_bf16 v[42:45], v[138:141], v[218:221], v[42:45]
	v_mfma_f32_16x16x32_bf16 v[38:41], v[142:145], v[214:217], v[38:41]
	v_mfma_f32_16x16x32_bf16 v[38:41], v[146:149], v[218:221], v[38:41]
	v_mfma_f32_16x16x32_bf16 v[34:37], v[150:153], v[166:169], v[34:37]
	v_mfma_f32_16x16x32_bf16 v[34:37], v[154:157], v[170:173], v[34:37]
	v_mfma_f32_16x16x32_bf16 v[30:33], v[158:161], v[166:169], v[30:33]
	v_mfma_f32_16x16x32_bf16 v[30:33], v[162:165], v[170:173], v[30:33]
	v_mfma_f32_16x16x32_bf16 v[26:29], v[150:153], v[174:177], v[26:29]
	v_mfma_f32_16x16x32_bf16 v[26:29], v[154:157], v[202:205], v[26:29]
	v_mfma_f32_16x16x32_bf16 v[22:25], v[158:161], v[174:177], v[22:25]
	v_mfma_f32_16x16x32_bf16 v[22:25], v[162:165], v[202:205], v[22:25]
	v_mfma_f32_16x16x32_bf16 v[18:21], v[150:153], v[206:209], v[18:21]
	v_mfma_f32_16x16x32_bf16 v[18:21], v[154:157], v[210:213], v[18:21]
	v_mfma_f32_16x16x32_bf16 v[14:17], v[158:161], v[206:209], v[14:17]
	v_mfma_f32_16x16x32_bf16 v[14:17], v[162:165], v[210:213], v[14:17]
	v_mfma_f32_16x16x32_bf16 v[10:13], v[150:153], v[214:217], v[10:13]
	v_mfma_f32_16x16x32_bf16 v[10:13], v[154:157], v[218:221], v[10:13]
	v_mfma_f32_16x16x32_bf16 v[6:9], v[158:161], v[214:217], v[6:9]
	v_mfma_f32_16x16x32_bf16 v[6:9], v[162:165], v[218:221], v[6:9]
	s_waitcnt vmcnt(8)
	s_barrier
	s_add_i32 s84, 0, 0x18000
	s_add_i32 s85, 0, 0x1c000
	ds_read_b128 v[134:137], v246
	ds_read_b128 v[138:141], v246 offset:1024
	ds_read_b128 v[142:145], v246 offset:2048
	ds_read_b128 v[146:149], v246 offset:3072
	ds_read_b128 v[150:153], v247
	ds_read_b128 v[154:157], v247 offset:1024
	ds_read_b128 v[158:161], v247 offset:2048
	ds_read_b128 v[162:165], v247 offset:3072
	s_add_u32 s100, s58, 0x80
	s_addc_u32 s101, s59, 0
	s_add_u32 s58, s58, 0x100000
	s_addc_u32 s59, s59, 0
	s_mov_b32 m0, s67
	ds_read_b128 v[166:169], v230 offset:32768
	ds_read_b128 v[170:173], v230 offset:33792
	ds_read_b128 v[174:177], v230 offset:34816
	ds_read_b128 v[202:205], v230 offset:35840
	ds_read_b128 v[206:209], v230 offset:36864
	ds_read_b128 v[210:213], v230 offset:37888
	ds_read_b128 v[214:217], v230 offset:38912
	ds_read_b128 v[218:221], v230 offset:39936
	global_load_lds_dwordx4 v178, s[58:59]
	s_mov_b32 m0, s68
	s_nop 0
	global_load_lds_dwordx4 v182, s[58:59]
	s_waitcnt lgkmcnt(0)
	s_barrier
	v_mfma_f32_16x16x32_bf16 v[2:5], v[134:137], v[166:169], v[2:5]
	v_mfma_f32_16x16x32_bf16 v[2:5], v[138:141], v[170:173], v[2:5]
	v_mfma_f32_16x16x32_bf16 v[126:129], v[142:145], v[166:169], v[126:129]
	v_mfma_f32_16x16x32_bf16 v[126:129], v[146:149], v[170:173], v[126:129]
	v_mfma_f32_16x16x32_bf16 v[122:125], v[134:137], v[174:177], v[122:125]
	v_mfma_f32_16x16x32_bf16 v[122:125], v[138:141], v[202:205], v[122:125]
	v_mfma_f32_16x16x32_bf16 v[118:121], v[142:145], v[174:177], v[118:121]
	v_mfma_f32_16x16x32_bf16 v[118:121], v[146:149], v[202:205], v[118:121]
	v_mfma_f32_16x16x32_bf16 v[114:117], v[134:137], v[206:209], v[114:117]
	v_mfma_f32_16x16x32_bf16 v[114:117], v[138:141], v[210:213], v[114:117]
	v_mfma_f32_16x16x32_bf16 v[110:113], v[142:145], v[206:209], v[110:113]
	v_mfma_f32_16x16x32_bf16 v[110:113], v[146:149], v[210:213], v[110:113]
	v_mfma_f32_16x16x32_bf16 v[106:109], v[134:137], v[214:217], v[106:109]
	v_mfma_f32_16x16x32_bf16 v[106:109], v[138:141], v[218:221], v[106:109]
	v_mfma_f32_16x16x32_bf16 v[102:105], v[142:145], v[214:217], v[102:105]
	v_mfma_f32_16x16x32_bf16 v[102:105], v[146:149], v[218:221], v[102:105]
	v_mfma_f32_16x16x32_bf16 v[98:101], v[150:153], v[166:169], v[98:101]
	v_mfma_f32_16x16x32_bf16 v[98:101], v[154:157], v[170:173], v[98:101]
	v_mfma_f32_16x16x32_bf16 v[94:97], v[158:161], v[166:169], v[94:97]
	v_mfma_f32_16x16x32_bf16 v[94:97], v[162:165], v[170:173], v[94:97]
	v_mfma_f32_16x16x32_bf16 v[90:93], v[150:153], v[174:177], v[90:93]
	v_mfma_f32_16x16x32_bf16 v[90:93], v[154:157], v[202:205], v[90:93]
	v_mfma_f32_16x16x32_bf16 v[86:89], v[158:161], v[174:177], v[86:89]
	v_mfma_f32_16x16x32_bf16 v[86:89], v[162:165], v[202:205], v[86:89]
	v_mfma_f32_16x16x32_bf16 v[82:85], v[150:153], v[206:209], v[82:85]
	v_mfma_f32_16x16x32_bf16 v[82:85], v[154:157], v[210:213], v[82:85]
	v_mfma_f32_16x16x32_bf16 v[78:81], v[158:161], v[206:209], v[78:81]
	v_mfma_f32_16x16x32_bf16 v[78:81], v[162:165], v[210:213], v[78:81]
	v_mfma_f32_16x16x32_bf16 v[74:77], v[150:153], v[214:217], v[74:77]
	v_mfma_f32_16x16x32_bf16 v[74:77], v[154:157], v[218:221], v[74:77]
	v_mfma_f32_16x16x32_bf16 v[70:73], v[158:161], v[214:217], v[70:73]
	v_mfma_f32_16x16x32_bf16 v[70:73], v[162:165], v[218:221], v[70:73]
	s_waitcnt vmcnt(8)
	s_barrier
	s_add_i32 s58, s84, s63
	s_add_u32 s98, s56, 0x80
	s_addc_u32 s99, s57, 0
	s_mov_b32 m0, s58
	ds_read_b128 v[166:169], v230 offset:49152
	ds_read_b128 v[170:173], v230 offset:50176
	ds_read_b128 v[174:177], v230 offset:51200
	ds_read_b128 v[202:205], v230 offset:52224
	ds_read_b128 v[206:209], v230 offset:53248
	ds_read_b128 v[210:213], v230 offset:54272
	ds_read_b128 v[214:217], v230 offset:55296
	ds_read_b128 v[218:221], v230 offset:56320
	global_load_lds_dwordx4 v180, s[98:99]
	s_add_i32 m0, s58, 0x2000
	s_add_u32 s56, s56, 0x100080
	s_addc_u32 s57, s57, 0
	s_add_i32 s58, s85, s63
	global_load_lds_dwordx4 v184, s[98:99]
	s_mov_b32 m0, s58
	s_nop 0
	global_load_lds_dwordx4 v180, s[56:57]
	s_add_i32 m0, s58, 0x2000
	s_nop 0
	global_load_lds_dwordx4 v184, s[56:57]
	s_mov_b32 m0, s74
	s_nop 0
	global_load_lds_dwordx4 v178, s[100:101]
	s_mov_b32 m0, s75
	s_nop 0
	global_load_lds_dwordx4 v182, s[100:101]
	s_waitcnt lgkmcnt(0)
	s_barrier
	v_mfma_f32_16x16x32_bf16 v[66:69], v[134:137], v[166:169], v[66:69]
	v_mfma_f32_16x16x32_bf16 v[66:69], v[138:141], v[170:173], v[66:69]
	v_mfma_f32_16x16x32_bf16 v[62:65], v[142:145], v[166:169], v[62:65]
	v_mfma_f32_16x16x32_bf16 v[62:65], v[146:149], v[170:173], v[62:65]
	v_mfma_f32_16x16x32_bf16 v[58:61], v[134:137], v[174:177], v[58:61]
	v_mfma_f32_16x16x32_bf16 v[58:61], v[138:141], v[202:205], v[58:61]
	v_mfma_f32_16x16x32_bf16 v[54:57], v[142:145], v[174:177], v[54:57]
	v_mfma_f32_16x16x32_bf16 v[54:57], v[146:149], v[202:205], v[54:57]
	v_mfma_f32_16x16x32_bf16 v[50:53], v[134:137], v[206:209], v[50:53]
	v_mfma_f32_16x16x32_bf16 v[50:53], v[138:141], v[210:213], v[50:53]
	v_mfma_f32_16x16x32_bf16 v[46:49], v[142:145], v[206:209], v[46:49]
	v_mfma_f32_16x16x32_bf16 v[46:49], v[146:149], v[210:213], v[46:49]
	v_mfma_f32_16x16x32_bf16 v[42:45], v[134:137], v[214:217], v[42:45]
	v_mfma_f32_16x16x32_bf16 v[42:45], v[138:141], v[218:221], v[42:45]
	v_mfma_f32_16x16x32_bf16 v[38:41], v[142:145], v[214:217], v[38:41]
	v_mfma_f32_16x16x32_bf16 v[38:41], v[146:149], v[218:221], v[38:41]
	v_mfma_f32_16x16x32_bf16 v[34:37], v[150:153], v[166:169], v[34:37]
	v_mfma_f32_16x16x32_bf16 v[34:37], v[154:157], v[170:173], v[34:37]
	v_mfma_f32_16x16x32_bf16 v[30:33], v[158:161], v[166:169], v[30:33]
	v_mfma_f32_16x16x32_bf16 v[30:33], v[162:165], v[170:173], v[30:33]
	v_mfma_f32_16x16x32_bf16 v[26:29], v[150:153], v[174:177], v[26:29]
	v_mfma_f32_16x16x32_bf16 v[26:29], v[154:157], v[202:205], v[26:29]
	v_mfma_f32_16x16x32_bf16 v[22:25], v[158:161], v[174:177], v[22:25]
	v_mfma_f32_16x16x32_bf16 v[22:25], v[162:165], v[202:205], v[22:25]
	v_mfma_f32_16x16x32_bf16 v[18:21], v[150:153], v[206:209], v[18:21]
	v_mfma_f32_16x16x32_bf16 v[18:21], v[154:157], v[210:213], v[18:21]
	v_mfma_f32_16x16x32_bf16 v[14:17], v[158:161], v[206:209], v[14:17]
	v_mfma_f32_16x16x32_bf16 v[14:17], v[162:165], v[210:213], v[14:17]
	v_mfma_f32_16x16x32_bf16 v[10:13], v[150:153], v[214:217], v[10:13]
	v_mfma_f32_16x16x32_bf16 v[10:13], v[154:157], v[218:221], v[10:13]
	v_mfma_f32_16x16x32_bf16 v[6:9], v[158:161], v[214:217], v[6:9]
	v_mfma_f32_16x16x32_bf16 v[6:9], v[162:165], v[218:221], v[6:9]
	s_waitcnt vmcnt(8)
	s_barrier
	s_add_i32 s83, s83, 2
	s_add_u32 s10, s10, 0x100
	s_addc_u32 s11, s11, 0
	s_cmp_gt_u32 s83, 61
	s_cbranch_scc0 .LBB0_1153
	s_and_b64 vcc, exec, s[36:37]
	s_cbranch_vccz .LBB0_1156
	s_barrier

.LBB0_1325:
	ds_read_b128 v[130:133], v176
	ds_read_b128 v[134:137], v176 offset:1024
	ds_read_b128 v[138:141], v176 offset:2048
	ds_read_b128 v[142:145], v176 offset:3072
	ds_read_b128 v[146:149], v177
	ds_read_b128 v[166:169], v177 offset:1024
	ds_read_b128 v[170:173], v177 offset:2048
	ds_read_b128 v[180:183], v177 offset:3072
	s_add_u32 s26, s24, 0xffd50080
	s_addc_u32 s27, s25, -1
	s_cmpk_eq_i32 s49, 0xa8
	s_cselect_b32 s29, s5, s27
	s_cselect_b32 s28, s4, s26
	s_cselect_b32 s27, s23, s48
	s_cselect_b32 s26, s22, s47
	s_add_i32 m0, s33, 0xc000
	ds_read_b128 v[184:187], v178
	ds_read_b128 v[188:191], v178 offset:1024
	ds_read_b128 v[192:195], v178 offset:2048
	ds_read_b128 v[196:199], v178 offset:3072
	ds_read_b128 v[200:203], v178 offset:4096
	ds_read_b128 v[204:207], v178 offset:5120
	ds_read_b128 v[208:211], v178 offset:6144
	ds_read_b128 v[212:215], v178 offset:7168
	global_load_lds_dwordx4 v158, s[24:25]
	s_add_i32 m0, s33, 0xe000
	s_nop 0
	global_load_lds_dwordx4 v160, s[24:25]
	s_waitcnt lgkmcnt(0)
	s_barrier
	v_mfma_f32_16x16x32_bf16 v[126:129], v[130:133], v[184:187], v[126:129]
	v_mfma_f32_16x16x32_bf16 v[126:129], v[134:137], v[188:191], v[126:129]
	v_mfma_f32_16x16x32_bf16 v[122:125], v[138:141], v[184:187], v[122:125]
	v_mfma_f32_16x16x32_bf16 v[122:125], v[142:145], v[188:191], v[122:125]
	v_mfma_f32_16x16x32_bf16 v[110:113], v[130:133], v[192:195], v[110:113]
	v_mfma_f32_16x16x32_bf16 v[110:113], v[134:137], v[196:199], v[110:113]
	v_mfma_f32_16x16x32_bf16 v[106:109], v[138:141], v[192:195], v[106:109]
	v_mfma_f32_16x16x32_bf16 v[106:109], v[142:145], v[196:199], v[106:109]
	v_mfma_f32_16x16x32_bf16 v[94:97], v[130:133], v[200:203], v[94:97]
	v_mfma_f32_16x16x32_bf16 v[94:97], v[134:137], v[204:207], v[94:97]
	v_mfma_f32_16x16x32_bf16 v[90:93], v[138:141], v[200:203], v[90:93]
	v_mfma_f32_16x16x32_bf16 v[90:93], v[142:145], v[204:207], v[90:93]
	v_mfma_f32_16x16x32_bf16 v[78:81], v[130:133], v[208:211], v[78:81]
	v_mfma_f32_16x16x32_bf16 v[78:81], v[134:137], v[212:215], v[78:81]
	v_mfma_f32_16x16x32_bf16 v[74:77], v[138:141], v[208:211], v[74:77]
	v_mfma_f32_16x16x32_bf16 v[74:77], v[142:145], v[212:215], v[74:77]
	v_mfma_f32_16x16x32_bf16 v[118:121], v[146:149], v[184:187], v[118:121]
	v_mfma_f32_16x16x32_bf16 v[118:121], v[166:169], v[188:191], v[118:121]
	v_mfma_f32_16x16x32_bf16 v[114:117], v[170:173], v[184:187], v[114:117]
	v_mfma_f32_16x16x32_bf16 v[114:117], v[180:183], v[188:191], v[114:117]
	v_mfma_f32_16x16x32_bf16 v[102:105], v[146:149], v[192:195], v[102:105]
	v_mfma_f32_16x16x32_bf16 v[102:105], v[166:169], v[196:199], v[102:105]
	v_mfma_f32_16x16x32_bf16 v[98:101], v[170:173], v[192:195], v[98:101]
	v_mfma_f32_16x16x32_bf16 v[98:101], v[180:183], v[196:199], v[98:101]
	v_mfma_f32_16x16x32_bf16 v[86:89], v[146:149], v[200:203], v[86:89]
	v_mfma_f32_16x16x32_bf16 v[86:89], v[166:169], v[204:207], v[86:89]
	v_mfma_f32_16x16x32_bf16 v[82:85], v[170:173], v[200:203], v[82:85]
	v_mfma_f32_16x16x32_bf16 v[82:85], v[180:183], v[204:207], v[82:85]
	v_mfma_f32_16x16x32_bf16 v[70:73], v[146:149], v[208:211], v[70:73]
	v_mfma_f32_16x16x32_bf16 v[70:73], v[166:169], v[212:215], v[70:73]
	v_mfma_f32_16x16x32_bf16 v[66:69], v[170:173], v[208:211], v[66:69]
	v_mfma_f32_16x16x32_bf16 v[66:69], v[180:183], v[212:215], v[66:69]
	s_waitcnt vmcnt(8)
	s_barrier
	s_add_i32 s50, s41, s31
	s_mov_b32 m0, s50
	ds_read_b128 v[184:187], v178 offset:16384
	ds_read_b128 v[188:191], v178 offset:17408
	ds_read_b128 v[192:195], v178 offset:18432
	ds_read_b128 v[196:199], v178 offset:19456
	ds_read_b128 v[200:203], v178 offset:20480
	ds_read_b128 v[204:207], v178 offset:21504
	ds_read_b128 v[208:211], v178 offset:22528
	ds_read_b128 v[212:215], v178 offset:23552
	global_load_lds_dwordx4 v152, s[26:27]
	s_add_i32 m0, s50, 0x2000
	s_add_u32 s50, s26, 0x2b0000
	s_addc_u32 s51, s27, 0
	s_add_i32 s52, s42, s31
	global_load_lds_dwordx4 v156, s[26:27]
	s_mov_b32 m0, s52
	global_load_lds_dwordx4 v152, s[50:51]
	s_add_i32 m0, s52, 0x2000
	s_nop 0
	global_load_lds_dwordx4 v156, s[50:51]
	s_mov_b32 m0, s33
	s_nop 0
	global_load_lds_dwordx4 v150, s[28:29]
	s_mov_b32 m0, s34
	s_nop 0
	global_load_lds_dwordx4 v154, s[28:29]
	s_waitcnt lgkmcnt(0)
	s_barrier
	v_mfma_f32_16x16x32_bf16 v[62:65], v[130:133], v[184:187], v[62:65]
	v_mfma_f32_16x16x32_bf16 v[62:65], v[134:137], v[188:191], v[62:65]
	v_mfma_f32_16x16x32_bf16 v[58:61], v[138:141], v[184:187], v[58:61]
	v_mfma_f32_16x16x32_bf16 v[58:61], v[142:145], v[188:191], v[58:61]
	v_mfma_f32_16x16x32_bf16 v[46:49], v[130:133], v[192:195], v[46:49]
	v_mfma_f32_16x16x32_bf16 v[46:49], v[134:137], v[196:199], v[46:49]
	v_mfma_f32_16x16x32_bf16 v[42:45], v[138:141], v[192:195], v[42:45]
	v_mfma_f32_16x16x32_bf16 v[42:45], v[142:145], v[196:199], v[42:45]
	v_mfma_f32_16x16x32_bf16 v[30:33], v[130:133], v[200:203], v[30:33]
	v_mfma_f32_16x16x32_bf16 v[30:33], v[134:137], v[204:207], v[30:33]
	v_mfma_f32_16x16x32_bf16 v[26:29], v[138:141], v[200:203], v[26:29]
	v_mfma_f32_16x16x32_bf16 v[26:29], v[142:145], v[204:207], v[26:29]
	v_mfma_f32_16x16x32_bf16 v[14:17], v[130:133], v[208:211], v[14:17]
	v_mfma_f32_16x16x32_bf16 v[14:17], v[134:137], v[212:215], v[14:17]
	v_mfma_f32_16x16x32_bf16 v[10:13], v[138:141], v[208:211], v[10:13]
	v_mfma_f32_16x16x32_bf16 v[10:13], v[142:145], v[212:215], v[10:13]
	v_mfma_f32_16x16x32_bf16 v[54:57], v[146:149], v[184:187], v[54:57]
	v_mfma_f32_16x16x32_bf16 v[54:57], v[166:169], v[188:191], v[54:57]
	v_mfma_f32_16x16x32_bf16 v[50:53], v[170:173], v[184:187], v[50:53]
	v_mfma_f32_16x16x32_bf16 v[50:53], v[180:183], v[188:191], v[50:53]
	v_mfma_f32_16x16x32_bf16 v[38:41], v[146:149], v[192:195], v[38:41]
	v_mfma_f32_16x16x32_bf16 v[38:41], v[166:169], v[196:199], v[38:41]
	v_mfma_f32_16x16x32_bf16 v[34:37], v[170:173], v[192:195], v[34:37]
	v_mfma_f32_16x16x32_bf16 v[34:37], v[180:183], v[196:199], v[34:37]
	v_mfma_f32_16x16x32_bf16 v[22:25], v[146:149], v[200:203], v[22:25]
	v_mfma_f32_16x16x32_bf16 v[22:25], v[166:169], v[204:207], v[22:25]
	v_mfma_f32_16x16x32_bf16 v[18:21], v[170:173], v[200:203], v[18:21]
	v_mfma_f32_16x16x32_bf16 v[18:21], v[180:183], v[204:207], v[18:21]
	v_mfma_f32_16x16x32_bf16 v[6:9], v[146:149], v[208:211], v[6:9]
	v_mfma_f32_16x16x32_bf16 v[6:9], v[166:169], v[212:215], v[6:9]
	v_mfma_f32_16x16x32_bf16 v[2:5], v[170:173], v[208:211], v[2:5]
	v_mfma_f32_16x16x32_bf16 v[2:5], v[180:183], v[212:215], v[2:5]
	s_waitcnt vmcnt(8)
	s_barrier
	s_add_i32 s50, 0, 0x18000
	s_add_i32 s51, 0, 0x1c000
	ds_read_b128 v[130:133], v246
	ds_read_b128 v[134:137], v246 offset:1024
	ds_read_b128 v[138:141], v246 offset:2048
	ds_read_b128 v[142:145], v246 offset:3072
	ds_read_b128 v[146:149], v247
	ds_read_b128 v[166:169], v247 offset:1024
	ds_read_b128 v[170:173], v247 offset:2048
	ds_read_b128 v[180:183], v247 offset:3072
	s_add_u32 s98, s28, 0x80
	s_addc_u32 s99, s29, 0
	s_add_u32 s28, s28, 0x2b0000
	s_addc_u32 s29, s29, 0
	s_mov_b32 m0, s35
	ds_read_b128 v[184:187], v178 offset:32768
	ds_read_b128 v[188:191], v178 offset:33792
	ds_read_b128 v[192:195], v178 offset:34816
	ds_read_b128 v[196:199], v178 offset:35840
	ds_read_b128 v[200:203], v178 offset:36864
	ds_read_b128 v[204:207], v178 offset:37888
	ds_read_b128 v[208:211], v178 offset:38912
	ds_read_b128 v[212:215], v178 offset:39936
	global_load_lds_dwordx4 v150, s[28:29]
	s_mov_b32 m0, s36
	s_nop 0
	global_load_lds_dwordx4 v154, s[28:29]
	s_waitcnt lgkmcnt(0)
	s_barrier
	v_mfma_f32_16x16x32_bf16 v[126:129], v[130:133], v[184:187], v[126:129]
	v_mfma_f32_16x16x32_bf16 v[126:129], v[134:137], v[188:191], v[126:129]
	v_mfma_f32_16x16x32_bf16 v[122:125], v[138:141], v[184:187], v[122:125]
	v_mfma_f32_16x16x32_bf16 v[122:125], v[142:145], v[188:191], v[122:125]
	v_mfma_f32_16x16x32_bf16 v[110:113], v[130:133], v[192:195], v[110:113]
	v_mfma_f32_16x16x32_bf16 v[110:113], v[134:137], v[196:199], v[110:113]
	v_mfma_f32_16x16x32_bf16 v[106:109], v[138:141], v[192:195], v[106:109]
	v_mfma_f32_16x16x32_bf16 v[106:109], v[142:145], v[196:199], v[106:109]
	v_mfma_f32_16x16x32_bf16 v[94:97], v[130:133], v[200:203], v[94:97]
	v_mfma_f32_16x16x32_bf16 v[94:97], v[134:137], v[204:207], v[94:97]
	v_mfma_f32_16x16x32_bf16 v[90:93], v[138:141], v[200:203], v[90:93]
	v_mfma_f32_16x16x32_bf16 v[90:93], v[142:145], v[204:207], v[90:93]
	v_mfma_f32_16x16x32_bf16 v[78:81], v[130:133], v[208:211], v[78:81]
	v_mfma_f32_16x16x32_bf16 v[78:81], v[134:137], v[212:215], v[78:81]
	v_mfma_f32_16x16x32_bf16 v[74:77], v[138:141], v[208:211], v[74:77]
	v_mfma_f32_16x16x32_bf16 v[74:77], v[142:145], v[212:215], v[74:77]
	v_mfma_f32_16x16x32_bf16 v[118:121], v[146:149], v[184:187], v[118:121]
	v_mfma_f32_16x16x32_bf16 v[118:121], v[166:169], v[188:191], v[118:121]
	v_mfma_f32_16x16x32_bf16 v[114:117], v[170:173], v[184:187], v[114:117]
	v_mfma_f32_16x16x32_bf16 v[114:117], v[180:183], v[188:191], v[114:117]
	v_mfma_f32_16x16x32_bf16 v[102:105], v[146:149], v[192:195], v[102:105]
	v_mfma_f32_16x16x32_bf16 v[102:105], v[166:169], v[196:199], v[102:105]
	v_mfma_f32_16x16x32_bf16 v[98:101], v[170:173], v[192:195], v[98:101]
	v_mfma_f32_16x16x32_bf16 v[98:101], v[180:183], v[196:199], v[98:101]
	v_mfma_f32_16x16x32_bf16 v[86:89], v[146:149], v[200:203], v[86:89]
	v_mfma_f32_16x16x32_bf16 v[86:89], v[166:169], v[204:207], v[86:89]
	v_mfma_f32_16x16x32_bf16 v[82:85], v[170:173], v[200:203], v[82:85]
	v_mfma_f32_16x16x32_bf16 v[82:85], v[180:183], v[204:207], v[82:85]
	v_mfma_f32_16x16x32_bf16 v[70:73], v[146:149], v[208:211], v[70:73]
	v_mfma_f32_16x16x32_bf16 v[70:73], v[166:169], v[212:215], v[70:73]
	v_mfma_f32_16x16x32_bf16 v[66:69], v[170:173], v[208:211], v[66:69]
	v_mfma_f32_16x16x32_bf16 v[66:69], v[180:183], v[212:215], v[66:69]
	s_waitcnt vmcnt(8)
	s_barrier
	s_add_i32 s28, s50, s31
	s_mov_b32 m0, s28
	ds_read_b128 v[184:187], v178 offset:49152
	ds_read_b128 v[188:191], v178 offset:50176
	ds_read_b128 v[192:195], v178 offset:51200
	ds_read_b128 v[196:199], v178 offset:52224
	ds_read_b128 v[200:203], v178 offset:53248
	ds_read_b128 v[204:207], v178 offset:54272
	ds_read_b128 v[208:211], v178 offset:55296
	ds_read_b128 v[212:215], v178 offset:56320
	s_add_u32 s26, s26, 0x80
	s_addc_u32 s27, s27, 0
	global_load_lds_dwordx4 v152, s[26:27]
	s_add_i32 m0, s28, 0x2000
	s_add_i32 s28, s51, s31
	global_load_lds_dwordx4 v156, s[26:27]
	s_add_u32 s26, s26, 0x2b0000
	s_addc_u32 s27, s27, 0
	s_mov_b32 m0, s28
	s_nop 0
	global_load_lds_dwordx4 v152, s[26:27]
	s_add_i32 m0, s28, 0x2000
	s_nop 0
	global_load_lds_dwordx4 v156, s[26:27]
	s_mov_b32 m0, s38
	s_nop 0
	global_load_lds_dwordx4 v150, s[98:99]
	s_mov_b32 m0, s39
	s_nop 0
	global_load_lds_dwordx4 v154, s[98:99]
	s_waitcnt lgkmcnt(0)
	s_barrier
	v_mfma_f32_16x16x32_bf16 v[62:65], v[130:133], v[184:187], v[62:65]
	v_mfma_f32_16x16x32_bf16 v[62:65], v[134:137], v[188:191], v[62:65]
	v_mfma_f32_16x16x32_bf16 v[58:61], v[138:141], v[184:187], v[58:61]
	v_mfma_f32_16x16x32_bf16 v[58:61], v[142:145], v[188:191], v[58:61]
	v_mfma_f32_16x16x32_bf16 v[46:49], v[130:133], v[192:195], v[46:49]
	v_mfma_f32_16x16x32_bf16 v[46:49], v[134:137], v[196:199], v[46:49]
	v_mfma_f32_16x16x32_bf16 v[42:45], v[138:141], v[192:195], v[42:45]
	v_mfma_f32_16x16x32_bf16 v[42:45], v[142:145], v[196:199], v[42:45]
	v_mfma_f32_16x16x32_bf16 v[30:33], v[130:133], v[200:203], v[30:33]
	v_mfma_f32_16x16x32_bf16 v[30:33], v[134:137], v[204:207], v[30:33]
	v_mfma_f32_16x16x32_bf16 v[26:29], v[138:141], v[200:203], v[26:29]
	v_mfma_f32_16x16x32_bf16 v[26:29], v[142:145], v[204:207], v[26:29]
	v_mfma_f32_16x16x32_bf16 v[14:17], v[130:133], v[208:211], v[14:17]
	v_mfma_f32_16x16x32_bf16 v[14:17], v[134:137], v[212:215], v[14:17]
	v_mfma_f32_16x16x32_bf16 v[10:13], v[138:141], v[208:211], v[10:13]
	v_mfma_f32_16x16x32_bf16 v[10:13], v[142:145], v[212:215], v[10:13]
	v_mfma_f32_16x16x32_bf16 v[54:57], v[146:149], v[184:187], v[54:57]
	v_mfma_f32_16x16x32_bf16 v[54:57], v[166:169], v[188:191], v[54:57]
	v_mfma_f32_16x16x32_bf16 v[50:53], v[170:173], v[184:187], v[50:53]
	v_mfma_f32_16x16x32_bf16 v[50:53], v[180:183], v[188:191], v[50:53]
	v_mfma_f32_16x16x32_bf16 v[38:41], v[146:149], v[192:195], v[38:41]
	v_mfma_f32_16x16x32_bf16 v[38:41], v[166:169], v[196:199], v[38:41]
	v_mfma_f32_16x16x32_bf16 v[34:37], v[170:173], v[192:195], v[34:37]
	v_mfma_f32_16x16x32_bf16 v[34:37], v[180:183], v[196:199], v[34:37]
	v_mfma_f32_16x16x32_bf16 v[22:25], v[146:149], v[200:203], v[22:25]
	v_mfma_f32_16x16x32_bf16 v[22:25], v[166:169], v[204:207], v[22:25]
	v_mfma_f32_16x16x32_bf16 v[18:21], v[170:173], v[200:203], v[18:21]
	v_mfma_f32_16x16x32_bf16 v[18:21], v[180:183], v[204:207], v[18:21]
	v_mfma_f32_16x16x32_bf16 v[6:9], v[146:149], v[208:211], v[6:9]
	v_mfma_f32_16x16x32_bf16 v[6:9], v[166:169], v[212:215], v[6:9]
	v_mfma_f32_16x16x32_bf16 v[2:5], v[170:173], v[208:211], v[2:5]
	v_mfma_f32_16x16x32_bf16 v[2:5], v[180:183], v[212:215], v[2:5]
	s_waitcnt vmcnt(8)
	s_barrier
	s_add_i32 s49, s49, 2
	s_add_u32 s24, s24, 0x100
	s_addc_u32 s25, s25, 0
	s_add_u32 s47, s47, 0x100
	s_addc_u32 s48, s48, 0
	s_cmpk_gt_u32 s49, 0xa9
	s_cbranch_scc0 .LBB0_1325
	s_and_b64 vcc, exec, s[10:11]
	s_cbranch_vccz .LBB0_1328
	s_barrier
